# GEMM K-loops: loop counter/pointer updates and next-iteration scalar head moved into the tail of the last load segment (before its wait); only the exit test follows the loop-back barrier
# speedup vs baseline: 1.0212x; 1.0032x over previous
; #define PG8_STAGE(bufoff, gbase, voff) do { _Pragma("unroll") for (int _i = 0; _i < 2; ++_i) \
;         __builtin_amdgcn_global_load_lds((const unsigned*)((const char*)(gbase) + (voff)[_i]), (PG8_LAS unsigned*)(lds + (bufoff) + ldsw + _i * 8192), 16, 0, 0); } while (0)
; #define PG8_LDA(dst, b, h) do { _Pragma("unroll") for (int m = 0; m < 4; ++m) _Pragma("unroll") for (int k = 0; k < 2; ++k) dst[m][k] = *(const PG8_LAS bf16x8*)(lds + PG8_SA(b, h) + aoff + m * 2048 + k * 1024); } while (0)
; #define PG8_MMA(ai, bj, At, Bt) do { __builtin_amdgcn_s_setprio(1); _Pragma("unroll") for (int m = 0; m < 4; ++m) _Pragma("unroll") for (int n = 0; n < 2; ++n) _Pragma("unroll") for (int k = 0; k < 2; ++k) \
;         acc[ai][bj][m][n] = __builtin_amdgcn_mfma_f32_16x16x32_bf16(Bt[n][k], At[m][k], acc[ai][bj][m][n], 0, 0, 0); __builtin_amdgcn_s_setprio(0); } while (0)
; #define PG8_WAIT_V(n) asm volatile("s_waitcnt vmcnt(" #n ")" ::: "memory")
; #define PG8_WAIT_L(n) asm volatile("s_waitcnt lgkmcnt(" #n ")" ::: "memory")
; #define PG8_BAR __builtin_amdgcn_s_barrier()
; #define PG8_SCHED __builtin_amdgcn_sched_barrier(0)
; template <class Epi, class Sched, bool ALIGN_EPI = false, bool SP2 = false>
; __device__ __forceinline__ void gemm_phase(PG8_LAS unsigned char* lds, const Gemm g, const Sched& S, const Epi& E) {
;     ...
;             PG8_WAIT_V(8); PG8_WAIT_L(0); PG8_BAR; PG8_MMA(0, 0, At, B0); PG8_MMA(0, 1, At, B1); PG8_BAR; PG8_SCHED;
;             PG8_LDA(At, 0, 1); PG8_STAGE(PG8_SB(0, 0), b2, voffB); PG8_STAGE(PG8_SB(0, 1), b2 + hstep, voffB); PG8_STAGE(PG8_SA(0, 0), a2, voffA);
;             PG8_WAIT_V(8); PG8_WAIT_L(0); PG8_BAR; PG8_MMA(1, 0, At, B0); PG8_MMA(1, 1, At, B1); PG8_BAR; PG8_SCHED;
.Lodin_noz:
	s_waitcnt vmcnt(8)
	s_waitcnt lgkmcnt(0)
	s_barrier
	s_setprio 1
	s_waitcnt lgkmcnt(0)
	v_mfma_f32_16x16x32_bf16 v[70:73], v[130:133], v[188:191], v[70:73]
	v_mfma_f32_16x16x32_bf16 v[66:69], v[158:161], v[188:191], v[66:69]
	v_mfma_f32_16x16x32_bf16 v[62:65], v[130:133], v[196:199], v[62:65]
	v_mfma_f32_16x16x32_bf16 v[58:61], v[158:161], v[196:199], v[58:61]
	v_mfma_f32_16x16x32_bf16 v[54:57], v[130:133], v[204:207], v[54:57]
	v_mfma_f32_16x16x32_bf16 v[50:53], v[158:161], v[204:207], v[50:53]
	v_mfma_f32_16x16x32_bf16 v[46:49], v[130:133], v[212:215], v[46:49]
	v_mfma_f32_16x16x32_bf16 v[42:45], v[158:161], v[212:215], v[42:45]
	v_mfma_f32_16x16x32_bf16 v[70:73], v[154:157], v[192:195], v[70:73]
	v_mfma_f32_16x16x32_bf16 v[66:69], v[162:165], v[192:195], v[66:69]
	v_mfma_f32_16x16x32_bf16 v[62:65], v[154:157], v[200:203], v[62:65]
	v_mfma_f32_16x16x32_bf16 v[58:61], v[162:165], v[200:203], v[58:61]
	v_mfma_f32_16x16x32_bf16 v[54:57], v[154:157], v[208:211], v[54:57]
	v_mfma_f32_16x16x32_bf16 v[50:53], v[162:165], v[208:211], v[50:53]
	v_mfma_f32_16x16x32_bf16 v[46:49], v[154:157], v[216:219], v[46:49]
	v_mfma_f32_16x16x32_bf16 v[42:45], v[162:165], v[216:219], v[42:45]
	v_mfma_f32_16x16x32_bf16 v[126:129], v[166:169], v[188:191], v[126:129]
	v_mfma_f32_16x16x32_bf16 v[122:125], v[180:183], v[188:191], v[122:125]
	v_mfma_f32_16x16x32_bf16 v[118:121], v[166:169], v[196:199], v[118:121]
	v_mfma_f32_16x16x32_bf16 v[114:117], v[180:183], v[196:199], v[114:117]
	v_mfma_f32_16x16x32_bf16 v[110:113], v[166:169], v[204:207], v[110:113]
	v_mfma_f32_16x16x32_bf16 v[106:109], v[180:183], v[204:207], v[106:109]
	v_mfma_f32_16x16x32_bf16 v[102:105], v[166:169], v[212:215], v[102:105]
	v_mfma_f32_16x16x32_bf16 v[98:101], v[180:183], v[212:215], v[98:101]
	v_mfma_f32_16x16x32_bf16 v[126:129], v[170:173], v[192:195], v[126:129]
	v_mfma_f32_16x16x32_bf16 v[122:125], v[184:187], v[192:195], v[122:125]
	v_mfma_f32_16x16x32_bf16 v[118:121], v[170:173], v[200:203], v[118:121]
	v_mfma_f32_16x16x32_bf16 v[114:117], v[184:187], v[200:203], v[114:117]
	v_mfma_f32_16x16x32_bf16 v[110:113], v[170:173], v[208:211], v[110:113]
	v_mfma_f32_16x16x32_bf16 v[106:109], v[184:187], v[208:211], v[106:109]
	v_mfma_f32_16x16x32_bf16 v[102:105], v[170:173], v[216:219], v[102:105]
	v_mfma_f32_16x16x32_bf16 v[98:101], v[184:187], v[216:219], v[98:101]
	s_setprio 0
	s_barrier
	s_add_i32 s55, s55, s39
	v_lshl_add_u64 v[146:147], s[30:31], 0, v[138:139]
	s_mov_b32 m0, s55
	ds_read_b128 v[188:191], v153 offset:16384
	ds_read_b128 v[192:195], v153 offset:17408
	ds_read_b128 v[196:199], v153 offset:18432
	ds_read_b128 v[200:203], v153 offset:19456
	ds_read_b128 v[204:207], v153 offset:20480
	ds_read_b128 v[208:211], v153 offset:21504
	ds_read_b128 v[212:215], v153 offset:22528
	ds_read_b128 v[216:219], v153 offset:23552
	global_load_lds_dwordx4 v[146:147], off
	s_add_i32 m0, s55, 0x2000
	s_add_u32 s56, s30, 0x40000
	v_lshl_add_u64 v[220:221], s[30:31], 0, v[134:135]
	s_addc_u32 s57, s31, 0
	s_add_i32 s55, s58, s39
	global_load_lds_dwordx4 v[220:221], off
	v_lshl_add_u64 v[222:223], s[56:57], 0, v[138:139]
	s_mov_b32 m0, s55
	v_lshl_add_u64 v[228:229], s[34:35], 0, v[136:137]
	global_load_lds_dwordx4 v[222:223], off
	v_lshl_add_u64 v[222:223], s[56:57], 0, v[134:135]
	s_add_i32 m0, s55, 0x2000
	s_nop 0
	global_load_lds_dwordx4 v[222:223], off
	v_lshl_add_u64 v[222:223], s[34:35], 0, v[140:141]
	s_mov_b32 m0, s40
	s_nop 0
	global_load_lds_dwordx4 v[222:223], off
	s_mov_b32 m0, s41
	s_nop 0
	global_load_lds_dwordx4 v[228:229], off
	s_waitcnt vmcnt(8)
	s_waitcnt lgkmcnt(0)
	s_barrier
	s_setprio 1
	s_waitcnt lgkmcnt(0)
	v_mfma_f32_16x16x32_bf16 v[30:33], v[130:133], v[188:191], v[30:33]
	v_mfma_f32_16x16x32_bf16 v[26:29], v[158:161], v[188:191], v[26:29]
	v_mfma_f32_16x16x32_bf16 v[22:25], v[130:133], v[196:199], v[22:25]
	v_mfma_f32_16x16x32_bf16 v[18:21], v[158:161], v[196:199], v[18:21]
	v_mfma_f32_16x16x32_bf16 v[14:17], v[130:133], v[204:207], v[14:17]
	v_mfma_f32_16x16x32_bf16 v[10:13], v[158:161], v[204:207], v[10:13]
	v_mfma_f32_16x16x32_bf16 v[6:9], v[130:133], v[212:215], v[6:9]
	v_mfma_f32_16x16x32_bf16 v[2:5], v[158:161], v[212:215], v[2:5]
	v_mfma_f32_16x16x32_bf16 v[30:33], v[154:157], v[192:195], v[30:33]
	v_mfma_f32_16x16x32_bf16 v[26:29], v[162:165], v[192:195], v[26:29]
	v_mfma_f32_16x16x32_bf16 v[22:25], v[154:157], v[200:203], v[22:25]
	v_mfma_f32_16x16x32_bf16 v[18:21], v[162:165], v[200:203], v[18:21]
	v_mfma_f32_16x16x32_bf16 v[14:17], v[154:157], v[208:211], v[14:17]
	v_mfma_f32_16x16x32_bf16 v[10:13], v[162:165], v[208:211], v[10:13]
	v_mfma_f32_16x16x32_bf16 v[6:9], v[154:157], v[216:219], v[6:9]
	v_mfma_f32_16x16x32_bf16 v[2:5], v[162:165], v[216:219], v[2:5]
	v_mfma_f32_16x16x32_bf16 v[94:97], v[166:169], v[188:191], v[94:97]
	v_mfma_f32_16x16x32_bf16 v[90:93], v[180:183], v[188:191], v[90:93]
	v_mfma_f32_16x16x32_bf16 v[86:89], v[166:169], v[196:199], v[86:89]
	v_mfma_f32_16x16x32_bf16 v[82:85], v[180:183], v[196:199], v[82:85]
	v_mfma_f32_16x16x32_bf16 v[78:81], v[166:169], v[204:207], v[78:81]
	v_mfma_f32_16x16x32_bf16 v[74:77], v[180:183], v[204:207], v[74:77]
	v_mfma_f32_16x16x32_bf16 v[38:41], v[166:169], v[212:215], v[38:41]
	v_mfma_f32_16x16x32_bf16 v[34:37], v[180:183], v[212:215], v[34:37]
	v_mfma_f32_16x16x32_bf16 v[94:97], v[170:173], v[192:195], v[94:97]
	v_mfma_f32_16x16x32_bf16 v[90:93], v[184:187], v[192:195], v[90:93]
	v_mfma_f32_16x16x32_bf16 v[86:89], v[170:173], v[200:203], v[86:89]
	v_mfma_f32_16x16x32_bf16 v[82:85], v[184:187], v[200:203], v[82:85]
	v_mfma_f32_16x16x32_bf16 v[78:81], v[170:173], v[208:211], v[78:81]
	v_mfma_f32_16x16x32_bf16 v[74:77], v[184:187], v[208:211], v[74:77]
	v_mfma_f32_16x16x32_bf16 v[38:41], v[170:173], v[216:219], v[38:41]
	v_mfma_f32_16x16x32_bf16 v[34:37], v[184:187], v[216:219], v[34:37]
	s_setprio 0
	s_barrier
; #define PG8_STAGE(bufoff, gbase, voff) do { _Pragma("unroll") for (int _i = 0; _i < 2; ++_i) \
;         __builtin_amdgcn_global_load_lds((const unsigned*)((const char*)(gbase) + (voff)[_i]), (PG8_LAS unsigned*)(lds + (bufoff) + ldsw + _i * 8192), 16, 0, 0); } while (0)
; #define PG8_LDA(dst, b, h) do { _Pragma("unroll") for (int m = 0; m < 4; ++m) _Pragma("unroll") for (int k = 0; k < 2; ++k) dst[m][k] = *(const PG8_LAS bf16x8*)(lds + PG8_SA(b, h) + aoff + m * 2048 + k * 1024); } while (0)
; #define PG8_LDB(dst, b, h) do { _Pragma("unroll") for (int n = 0; n < 2; ++n) _Pragma("unroll") for (int k = 0; k < 2; ++k) dst[n][k] = *(const PG8_LAS bf16x8*)(lds + PG8_SB(b, h) + boff + n * 2048 + k * 1024); } while (0)
; #define PG8_MMA(ai, bj, At, Bt) do { __builtin_amdgcn_s_setprio(1); _Pragma("unroll") for (int m = 0; m < 4; ++m) _Pragma("unroll") for (int n = 0; n < 2; ++n) _Pragma("unroll") for (int k = 0; k < 2; ++k) \
;         acc[ai][bj][m][n] = __builtin_amdgcn_mfma_f32_16x16x32_bf16(Bt[n][k], At[m][k], acc[ai][bj][m][n], 0, 0, 0); __builtin_amdgcn_s_setprio(0); } while (0)
; #define PG8_WAIT_V(n) asm volatile("s_waitcnt vmcnt(" #n ")" ::: "memory")
; #define PG8_WAIT_L(n) asm volatile("s_waitcnt lgkmcnt(" #n ")" ::: "memory")
; #define PG8_BAR __builtin_amdgcn_s_barrier()
; #define PG8_SCHED __builtin_amdgcn_sched_barrier(0)
; template <class Epi, class Sched, bool ALIGN_EPI = false, bool SP2 = false>
; __device__ __forceinline__ void gemm_phase(PG8_LAS unsigned char* lds, const Gemm g, const Sched& S, const Epi& E) {
;     ...
;             PG8_LDB(B0, 1, 0); PG8_LDB(B1, 1, 1); PG8_SCHED; PG8_LDA(At, 1, 0); PG8_STAGE(PG8_SA(0, 1), a2 + hstep, voffA);
;             PG8_WAIT_V(8); PG8_WAIT_L(0); PG8_BAR; PG8_MMA(0, 0, At, B0); PG8_MMA(0, 1, At, B1); PG8_BAR; PG8_SCHED;
	s_add_i32 s55, 0, 0x18000
	v_add_u32_e32 v148, s55, v151
	s_add_i32 s56, 0, 0x1c000
	ds_read_b128 v[130:133], v148
	ds_read_b128 v[154:157], v148 offset:1024
	ds_read_b128 v[158:161], v148 offset:2048
	ds_read_b128 v[162:165], v148 offset:3072
	v_add_u32_e32 v148, s56, v151
	ds_read_b128 v[166:169], v148
	ds_read_b128 v[170:173], v148 offset:1024
	ds_read_b128 v[180:183], v148 offset:2048
	ds_read_b128 v[184:187], v148 offset:3072
	s_add_u32 s34, s34, 0x40000
	s_addc_u32 s35, s35, 0
	s_mov_b32 m0, s42
	v_lshl_add_u64 v[230:231], s[34:35], 0, v[140:141]
	ds_read_b128 v[188:191], v153 offset:32768
	ds_read_b128 v[192:195], v153 offset:33792
	ds_read_b128 v[196:199], v153 offset:34816
	ds_read_b128 v[200:203], v153 offset:35840
	ds_read_b128 v[204:207], v153 offset:36864
	ds_read_b128 v[208:211], v153 offset:37888
	ds_read_b128 v[212:215], v153 offset:38912
	ds_read_b128 v[216:219], v153 offset:39936
	global_load_lds_dwordx4 v[230:231], off
	v_lshl_add_u64 v[230:231], s[34:35], 0, v[136:137]
	s_mov_b32 m0, s43
	s_nop 0
	global_load_lds_dwordx4 v[230:231], off
	s_waitcnt vmcnt(8)
	s_waitcnt lgkmcnt(0)
	s_barrier
	s_setprio 1
	s_waitcnt lgkmcnt(0)
	v_mfma_f32_16x16x32_bf16 v[70:73], v[130:133], v[188:191], v[70:73]
	v_mfma_f32_16x16x32_bf16 v[66:69], v[158:161], v[188:191], v[66:69]
	v_mfma_f32_16x16x32_bf16 v[62:65], v[130:133], v[196:199], v[62:65]
	v_mfma_f32_16x16x32_bf16 v[58:61], v[158:161], v[196:199], v[58:61]
	v_mfma_f32_16x16x32_bf16 v[54:57], v[130:133], v[204:207], v[54:57]
	v_mfma_f32_16x16x32_bf16 v[50:53], v[158:161], v[204:207], v[50:53]
	v_mfma_f32_16x16x32_bf16 v[46:49], v[130:133], v[212:215], v[46:49]
	v_mfma_f32_16x16x32_bf16 v[42:45], v[158:161], v[212:215], v[42:45]
	v_mfma_f32_16x16x32_bf16 v[70:73], v[154:157], v[192:195], v[70:73]
	v_mfma_f32_16x16x32_bf16 v[66:69], v[162:165], v[192:195], v[66:69]
	v_mfma_f32_16x16x32_bf16 v[62:65], v[154:157], v[200:203], v[62:65]
	v_mfma_f32_16x16x32_bf16 v[58:61], v[162:165], v[200:203], v[58:61]
	v_mfma_f32_16x16x32_bf16 v[54:57], v[154:157], v[208:211], v[54:57]
	v_mfma_f32_16x16x32_bf16 v[50:53], v[162:165], v[208:211], v[50:53]
	v_mfma_f32_16x16x32_bf16 v[46:49], v[154:157], v[216:219], v[46:49]
	v_mfma_f32_16x16x32_bf16 v[42:45], v[162:165], v[216:219], v[42:45]
	v_mfma_f32_16x16x32_bf16 v[126:129], v[166:169], v[188:191], v[126:129]
	v_mfma_f32_16x16x32_bf16 v[122:125], v[180:183], v[188:191], v[122:125]
	v_mfma_f32_16x16x32_bf16 v[118:121], v[166:169], v[196:199], v[118:121]
	v_mfma_f32_16x16x32_bf16 v[114:117], v[180:183], v[196:199], v[114:117]
	v_mfma_f32_16x16x32_bf16 v[110:113], v[166:169], v[204:207], v[110:113]
	v_mfma_f32_16x16x32_bf16 v[106:109], v[180:183], v[204:207], v[106:109]
	v_mfma_f32_16x16x32_bf16 v[102:105], v[166:169], v[212:215], v[102:105]
	v_mfma_f32_16x16x32_bf16 v[98:101], v[180:183], v[212:215], v[98:101]
	v_mfma_f32_16x16x32_bf16 v[126:129], v[170:173], v[192:195], v[126:129]
	v_mfma_f32_16x16x32_bf16 v[122:125], v[184:187], v[192:195], v[122:125]
	v_mfma_f32_16x16x32_bf16 v[118:121], v[170:173], v[200:203], v[118:121]
	v_mfma_f32_16x16x32_bf16 v[114:117], v[184:187], v[200:203], v[114:117]
	v_mfma_f32_16x16x32_bf16 v[110:113], v[170:173], v[208:211], v[110:113]
	v_mfma_f32_16x16x32_bf16 v[106:109], v[184:187], v[208:211], v[106:109]
	v_mfma_f32_16x16x32_bf16 v[102:105], v[170:173], v[216:219], v[102:105]
	v_mfma_f32_16x16x32_bf16 v[98:101], v[184:187], v[216:219], v[98:101]
	s_setprio 0
	s_barrier
; #define PG8_STAGE(bufoff, gbase, voff) do { _Pragma("unroll") for (int _i = 0; _i < 2; ++_i) \
;         __builtin_amdgcn_global_load_lds((const unsigned*)((const char*)(gbase) + (voff)[_i]), (PG8_LAS unsigned*)(lds + (bufoff) + ldsw + _i * 8192), 16, 0, 0); } while (0)
; #define PG8_LDA(dst, b, h) do { _Pragma("unroll") for (int m = 0; m < 4; ++m) _Pragma("unroll") for (int k = 0; k < 2; ++k) dst[m][k] = *(const PG8_LAS bf16x8*)(lds + PG8_SA(b, h) + aoff + m * 2048 + k * 1024); } while (0)
; #define PG8_MMA(ai, bj, At, Bt) do { __builtin_amdgcn_s_setprio(1); _Pragma("unroll") for (int m = 0; m < 4; ++m) _Pragma("unroll") for (int n = 0; n < 2; ++n) _Pragma("unroll") for (int k = 0; k < 2; ++k) \
;         acc[ai][bj][m][n] = __builtin_amdgcn_mfma_f32_16x16x32_bf16(Bt[n][k], At[m][k], acc[ai][bj][m][n], 0, 0, 0); __builtin_amdgcn_s_setprio(0); } while (0)
; #define PG8_WAIT_V(n) asm volatile("s_waitcnt vmcnt(" #n ")" ::: "memory")
; #define PG8_WAIT_L(n) asm volatile("s_waitcnt lgkmcnt(" #n ")" ::: "memory")
; #define PG8_BAR __builtin_amdgcn_s_barrier()
; #define PG8_SCHED __builtin_amdgcn_sched_barrier(0)
; template <class Epi, class Sched, bool ALIGN_EPI = false, bool SP2 = false>
; __device__ __forceinline__ void gemm_phase(PG8_LAS unsigned char* lds, const Gemm g, const Sched& S, const Epi& E) {
;     ...
;         for (int t = 0; t < nt; t += 2) {
;             const bool last = (t == nt - 2);
;             const char* a1 = cA + (size_t)(t + 1) * kstep;
;             const char* a2 = last ? nA : cA + (size_t)(t + 2) * kstep; const char* b2 = last ? nB : cB + (size_t)(t + 2) * kstep;
;             const char* a3 = a2 + kstep; const char* b3 = b2 + kstep;
;     ...
;             PG8_LDA(At, 1, 1); PG8_STAGE(PG8_SB(1, 0), b3, voffB); PG8_STAGE(PG8_SB(1, 1), b3 + hstep, voffB); PG8_STAGE(PG8_SA(1, 0), a3, voffA);
;             PG8_WAIT_V(8); PG8_WAIT_L(0); PG8_BAR; PG8_MMA(1, 0, At, B0); PG8_MMA(1, 1, At, B1); PG8_BAR; PG8_SCHED;
	s_add_i32 s34, s55, s39
	v_lshl_add_u64 v[146:147], v[146:147], 0, s[96:97]
	s_mov_b32 m0, s34
	ds_read_b128 v[188:191], v153 offset:49152
	ds_read_b128 v[192:195], v153 offset:50176
	ds_read_b128 v[196:199], v153 offset:51200
	ds_read_b128 v[200:203], v153 offset:52224
	ds_read_b128 v[204:207], v153 offset:53248
	ds_read_b128 v[208:211], v153 offset:54272
	ds_read_b128 v[212:215], v153 offset:55296
	ds_read_b128 v[216:219], v153 offset:56320
	global_load_lds_dwordx4 v[146:147], off
	s_add_i32 m0, s34, 0x2000
	s_add_u32 s30, s30, 0x40080
	v_lshl_add_u64 v[146:147], v[220:221], 0, s[96:97]
	s_addc_u32 s31, s31, 0
	s_add_i32 s34, s56, s39
	global_load_lds_dwordx4 v[146:147], off
	v_lshl_add_u64 v[146:147], s[30:31], 0, v[138:139]
	s_mov_b32 m0, s34
	s_nop 0
	global_load_lds_dwordx4 v[146:147], off
	v_lshl_add_u64 v[146:147], s[30:31], 0, v[134:135]
	s_add_i32 m0, s34, 0x2000
	s_nop 0
	global_load_lds_dwordx4 v[146:147], off
	v_lshl_add_u64 v[146:147], v[222:223], 0, s[96:97]
	s_mov_b32 m0, s48
	s_nop 0
	global_load_lds_dwordx4 v[146:147], off
	v_lshl_add_u64 v[146:147], v[228:229], 0, s[96:97]
	s_mov_b32 m0, s49
	s_nop 0
	global_load_lds_dwordx4 v[146:147], off
	s_add_i32 s54, s54, 2
	s_add_u32 s28, s28, 0x100
	s_addc_u32 s29, s29, 0
	s_add_u32 s52, s52, 0x100
	s_addc_u32 s53, s53, 0
	s_add_u32 s30, s28, 0xfffc0080
	s_addc_u32 s31, s29, -1
	s_add_i32 s55, 0, 0x10000
	s_cmp_eq_u32 s54, 12
	s_cselect_b32 s35, s23, s31
	s_cselect_b32 s34, s33, s30
	s_cselect_b32 s31, s21, s53
	s_cselect_b32 s30, s51, s52
	s_add_i32 s58, 0, 0x14000
	s_waitcnt vmcnt(8)
	s_waitcnt lgkmcnt(0)
	s_barrier
	s_setprio 1
	s_waitcnt lgkmcnt(0)
	v_mfma_f32_16x16x32_bf16 v[30:33], v[130:133], v[188:191], v[30:33]
	v_mfma_f32_16x16x32_bf16 v[26:29], v[158:161], v[188:191], v[26:29]
	v_mfma_f32_16x16x32_bf16 v[22:25], v[130:133], v[196:199], v[22:25]
	v_mfma_f32_16x16x32_bf16 v[18:21], v[158:161], v[196:199], v[18:21]
	v_mfma_f32_16x16x32_bf16 v[14:17], v[130:133], v[204:207], v[14:17]
	v_mfma_f32_16x16x32_bf16 v[10:13], v[158:161], v[204:207], v[10:13]
	v_mfma_f32_16x16x32_bf16 v[6:9], v[130:133], v[212:215], v[6:9]
	v_mfma_f32_16x16x32_bf16 v[2:5], v[158:161], v[212:215], v[2:5]
	v_mfma_f32_16x16x32_bf16 v[30:33], v[154:157], v[192:195], v[30:33]
	v_mfma_f32_16x16x32_bf16 v[26:29], v[162:165], v[192:195], v[26:29]
	v_mfma_f32_16x16x32_bf16 v[22:25], v[154:157], v[200:203], v[22:25]
	v_mfma_f32_16x16x32_bf16 v[18:21], v[162:165], v[200:203], v[18:21]
	v_mfma_f32_16x16x32_bf16 v[14:17], v[154:157], v[208:211], v[14:17]
	v_mfma_f32_16x16x32_bf16 v[10:13], v[162:165], v[208:211], v[10:13]
	v_mfma_f32_16x16x32_bf16 v[6:9], v[154:157], v[216:219], v[6:9]
	v_mfma_f32_16x16x32_bf16 v[2:5], v[162:165], v[216:219], v[2:5]
	v_mfma_f32_16x16x32_bf16 v[94:97], v[166:169], v[188:191], v[94:97]
	v_mfma_f32_16x16x32_bf16 v[90:93], v[180:183], v[188:191], v[90:93]
	v_mfma_f32_16x16x32_bf16 v[86:89], v[166:169], v[196:199], v[86:89]
	v_mfma_f32_16x16x32_bf16 v[82:85], v[180:183], v[196:199], v[82:85]
	v_mfma_f32_16x16x32_bf16 v[78:81], v[166:169], v[204:207], v[78:81]
	v_mfma_f32_16x16x32_bf16 v[74:77], v[180:183], v[204:207], v[74:77]
	v_mfma_f32_16x16x32_bf16 v[38:41], v[166:169], v[212:215], v[38:41]
	v_mfma_f32_16x16x32_bf16 v[34:37], v[180:183], v[212:215], v[34:37]
	v_mfma_f32_16x16x32_bf16 v[94:97], v[170:173], v[192:195], v[94:97]
	v_mfma_f32_16x16x32_bf16 v[90:93], v[184:187], v[192:195], v[90:93]
	v_mfma_f32_16x16x32_bf16 v[86:89], v[170:173], v[200:203], v[86:89]
	v_mfma_f32_16x16x32_bf16 v[82:85], v[184:187], v[200:203], v[82:85]
	v_mfma_f32_16x16x32_bf16 v[78:81], v[170:173], v[208:211], v[78:81]
	v_mfma_f32_16x16x32_bf16 v[74:77], v[184:187], v[208:211], v[74:77]
	v_mfma_f32_16x16x32_bf16 v[38:41], v[170:173], v[216:219], v[38:41]
	v_mfma_f32_16x16x32_bf16 v[34:37], v[184:187], v[216:219], v[34:37]
	s_setprio 0
	s_barrier
	s_cmp_gt_u32 s54, 13
	s_cbranch_scc0 .Lrot_odin
	s_and_b64 vcc, exec, s[16:17]
	s_cbranch_vccz .LBB0_188
	s_barrier

; #define PG8_STAGE(bufoff, gbase, voff) do { _Pragma("unroll") for (int _i = 0; _i < 2; ++_i) \
;         __builtin_amdgcn_global_load_lds((const unsigned*)((const char*)(gbase) + (voff)[_i]), (PG8_LAS unsigned*)(lds + (bufoff) + ldsw + _i * 8192), 16, 0, 0); } while (0)
; #define PG8_LDA(dst, b, h) do { _Pragma("unroll") for (int m = 0; m < 4; ++m) _Pragma("unroll") for (int k = 0; k < 2; ++k) dst[m][k] = *(const PG8_LAS bf16x8*)(lds + PG8_SA(b, h) + aoff + m * 2048 + k * 1024); } while (0)
; #define PG8_MMA(ai, bj, At, Bt) do { __builtin_amdgcn_s_setprio(1); _Pragma("unroll") for (int m = 0; m < 4; ++m) _Pragma("unroll") for (int n = 0; n < 2; ++n) _Pragma("unroll") for (int k = 0; k < 2; ++k) \
;         acc[ai][bj][m][n] = __builtin_amdgcn_mfma_f32_16x16x32_bf16(Bt[n][k], At[m][k], acc[ai][bj][m][n], 0, 0, 0); __builtin_amdgcn_s_setprio(0); } while (0)
; #define PG8_WAIT_V(n) asm volatile("s_waitcnt vmcnt(" #n ")" ::: "memory")
; #define PG8_WAIT_L(n) asm volatile("s_waitcnt lgkmcnt(" #n ")" ::: "memory")
; #define PG8_BAR __builtin_amdgcn_s_barrier()
; #define PG8_SCHED __builtin_amdgcn_sched_barrier(0)
; template <class Epi, class Sched, bool ALIGN_EPI = false, bool SP2 = false>
; __device__ __forceinline__ void gemm_phase(PG8_LAS unsigned char* lds, const Gemm g, const Sched& S, const Epi& E) {
;     ...
;             PG8_WAIT_V(8); PG8_WAIT_L(0); PG8_BAR; PG8_MMA(0, 0, At, B0); PG8_MMA(0, 1, At, B1); PG8_BAR; PG8_SCHED;
;             PG8_LDA(At, 0, 1); PG8_STAGE(PG8_SB(0, 0), b2, voffB); PG8_STAGE(PG8_SB(0, 1), b2 + hstep, voffB); PG8_STAGE(PG8_SA(0, 0), a2, voffA);
;             PG8_WAIT_V(8); PG8_WAIT_L(0); PG8_BAR; PG8_MMA(1, 0, At, B0); PG8_MMA(1, 1, At, B1); PG8_BAR; PG8_SCHED;
.Lodout_noz:
	s_waitcnt vmcnt(8)
	s_waitcnt lgkmcnt(0)
	s_barrier
	s_setprio 1
	s_waitcnt lgkmcnt(0)
	v_mfma_f32_16x16x32_bf16 v[158:161], v[66:69], v[162:165], v[158:161]
	v_mfma_f32_16x16x32_bf16 v[154:157], v[82:85], v[162:165], v[154:157]
	v_mfma_f32_16x16x32_bf16 v[142:145], v[66:69], v[188:191], v[142:145]
	v_mfma_f32_16x16x32_bf16 v[138:141], v[82:85], v[188:191], v[138:141]
	v_mfma_f32_16x16x32_bf16 v[114:117], v[66:69], v[196:199], v[114:117]
	v_mfma_f32_16x16x32_bf16 v[110:113], v[82:85], v[196:199], v[110:113]
	v_mfma_f32_16x16x32_bf16 v[90:93], v[66:69], v[210:213], v[90:93]
	v_mfma_f32_16x16x32_bf16 v[86:89], v[82:85], v[210:213], v[86:89]
	v_mfma_f32_16x16x32_bf16 v[158:161], v[70:73], v[166:169], v[158:161]
	v_mfma_f32_16x16x32_bf16 v[154:157], v[94:97], v[166:169], v[154:157]
	v_mfma_f32_16x16x32_bf16 v[142:145], v[70:73], v[192:195], v[142:145]
	v_mfma_f32_16x16x32_bf16 v[138:141], v[94:97], v[192:195], v[138:141]
	v_mfma_f32_16x16x32_bf16 v[114:117], v[70:73], v[206:209], v[114:117]
	v_mfma_f32_16x16x32_bf16 v[110:113], v[94:97], v[206:209], v[110:113]
	v_mfma_f32_16x16x32_bf16 v[90:93], v[70:73], v[214:217], v[90:93]
	v_mfma_f32_16x16x32_bf16 v[86:89], v[94:97], v[214:217], v[86:89]
	v_mfma_f32_16x16x32_bf16 v[150:153], v[106:109], v[162:165], v[150:153]
	v_mfma_f32_16x16x32_bf16 v[146:149], v[130:133], v[162:165], v[146:149]
	v_mfma_f32_16x16x32_bf16 v[126:129], v[106:109], v[188:191], v[126:129]
	v_mfma_f32_16x16x32_bf16 v[122:125], v[130:133], v[188:191], v[122:125]
	v_mfma_f32_16x16x32_bf16 v[102:105], v[106:109], v[196:199], v[102:105]
	v_mfma_f32_16x16x32_bf16 v[98:101], v[130:133], v[196:199], v[98:101]
	v_mfma_f32_16x16x32_bf16 v[78:81], v[106:109], v[210:213], v[78:81]
	v_mfma_f32_16x16x32_bf16 v[74:77], v[130:133], v[210:213], v[74:77]
	v_mfma_f32_16x16x32_bf16 v[150:153], v[118:121], v[166:169], v[150:153]
	v_mfma_f32_16x16x32_bf16 v[146:149], v[134:137], v[166:169], v[146:149]
	v_mfma_f32_16x16x32_bf16 v[126:129], v[118:121], v[192:195], v[126:129]
	v_mfma_f32_16x16x32_bf16 v[122:125], v[134:137], v[192:195], v[122:125]
	v_mfma_f32_16x16x32_bf16 v[102:105], v[118:121], v[206:209], v[102:105]
	v_mfma_f32_16x16x32_bf16 v[98:101], v[134:137], v[206:209], v[98:101]
	v_mfma_f32_16x16x32_bf16 v[78:81], v[118:121], v[214:217], v[78:81]
	v_mfma_f32_16x16x32_bf16 v[74:77], v[134:137], v[214:217], v[74:77]
	s_setprio 0
	s_barrier
	s_add_i32 s56, s56, s42
	v_lshl_add_u64 v[200:201], s[12:13], 0, v[180:181]
	s_mov_b32 m0, s56
	ds_read_b128 v[162:165], v204 offset:16384
	ds_read_b128 v[166:169], v204 offset:17408
	ds_read_b128 v[188:191], v204 offset:18432
	ds_read_b128 v[192:195], v204 offset:19456
	ds_read_b128 v[196:199], v204 offset:20480
	ds_read_b128 v[206:209], v204 offset:21504
	ds_read_b128 v[210:213], v204 offset:22528
	ds_read_b128 v[214:217], v204 offset:23552
	global_load_lds_dwordx4 v[200:201], off
	s_add_i32 m0, s56, 0x2000
	s_add_u32 s56, s12, 0x40000
	v_lshl_add_u64 v[218:219], s[12:13], 0, v[170:171]
	s_addc_u32 s57, s13, 0
	s_add_i32 s58, s58, s42
	global_load_lds_dwordx4 v[218:219], off
	v_lshl_add_u64 v[220:221], s[56:57], 0, v[180:181]
	s_mov_b32 m0, s58
	v_lshl_add_u64 v[222:223], s[36:37], 0, v[172:173]
	global_load_lds_dwordx4 v[220:221], off
	v_lshl_add_u64 v[220:221], s[56:57], 0, v[170:171]
	s_add_i32 m0, s58, 0x2000
	s_nop 0
	global_load_lds_dwordx4 v[220:221], off
	v_lshl_add_u64 v[220:221], s[36:37], 0, v[182:183]
	s_mov_b32 m0, s43
	s_nop 0
	global_load_lds_dwordx4 v[220:221], off
	s_mov_b32 m0, s44
	s_nop 0
	global_load_lds_dwordx4 v[222:223], off
	s_waitcnt vmcnt(8)
	s_waitcnt lgkmcnt(0)
	s_barrier
	s_setprio 1
	s_waitcnt lgkmcnt(0)
	v_mfma_f32_16x16x32_bf16 v[62:65], v[66:69], v[162:165], v[62:65]
	v_mfma_f32_16x16x32_bf16 v[58:61], v[82:85], v[162:165], v[58:61]
	v_mfma_f32_16x16x32_bf16 v[46:49], v[66:69], v[188:191], v[46:49]
	v_mfma_f32_16x16x32_bf16 v[42:45], v[82:85], v[188:191], v[42:45]
	v_mfma_f32_16x16x32_bf16 v[30:33], v[66:69], v[196:199], v[30:33]
	v_mfma_f32_16x16x32_bf16 v[26:29], v[82:85], v[196:199], v[26:29]
	v_mfma_f32_16x16x32_bf16 v[14:17], v[66:69], v[210:213], v[14:17]
	v_mfma_f32_16x16x32_bf16 v[10:13], v[82:85], v[210:213], v[10:13]
	v_mfma_f32_16x16x32_bf16 v[62:65], v[70:73], v[166:169], v[62:65]
	v_mfma_f32_16x16x32_bf16 v[58:61], v[94:97], v[166:169], v[58:61]
	v_mfma_f32_16x16x32_bf16 v[46:49], v[70:73], v[192:195], v[46:49]
	v_mfma_f32_16x16x32_bf16 v[42:45], v[94:97], v[192:195], v[42:45]
	v_mfma_f32_16x16x32_bf16 v[30:33], v[70:73], v[206:209], v[30:33]
	v_mfma_f32_16x16x32_bf16 v[26:29], v[94:97], v[206:209], v[26:29]
	v_mfma_f32_16x16x32_bf16 v[14:17], v[70:73], v[214:217], v[14:17]
	v_mfma_f32_16x16x32_bf16 v[10:13], v[94:97], v[214:217], v[10:13]
	v_mfma_f32_16x16x32_bf16 v[54:57], v[106:109], v[162:165], v[54:57]
	v_mfma_f32_16x16x32_bf16 v[50:53], v[130:133], v[162:165], v[50:53]
	v_mfma_f32_16x16x32_bf16 v[38:41], v[106:109], v[188:191], v[38:41]
	v_mfma_f32_16x16x32_bf16 v[34:37], v[130:133], v[188:191], v[34:37]
	v_mfma_f32_16x16x32_bf16 v[22:25], v[106:109], v[196:199], v[22:25]
	v_mfma_f32_16x16x32_bf16 v[18:21], v[130:133], v[196:199], v[18:21]
	v_mfma_f32_16x16x32_bf16 v[6:9], v[106:109], v[210:213], v[6:9]
	v_mfma_f32_16x16x32_bf16 v[2:5], v[130:133], v[210:213], v[2:5]
	v_mfma_f32_16x16x32_bf16 v[54:57], v[118:121], v[166:169], v[54:57]
	v_mfma_f32_16x16x32_bf16 v[50:53], v[134:137], v[166:169], v[50:53]
	v_mfma_f32_16x16x32_bf16 v[38:41], v[118:121], v[192:195], v[38:41]
	v_mfma_f32_16x16x32_bf16 v[34:37], v[134:137], v[192:195], v[34:37]
	v_mfma_f32_16x16x32_bf16 v[22:25], v[118:121], v[206:209], v[22:25]
	v_mfma_f32_16x16x32_bf16 v[18:21], v[134:137], v[206:209], v[18:21]
	v_mfma_f32_16x16x32_bf16 v[6:9], v[118:121], v[214:217], v[6:9]
	v_mfma_f32_16x16x32_bf16 v[2:5], v[134:137], v[214:217], v[2:5]
	s_setprio 0
	s_barrier
; #define PG8_STAGE(bufoff, gbase, voff) do { _Pragma("unroll") for (int _i = 0; _i < 2; ++_i) \
;         __builtin_amdgcn_global_load_lds((const unsigned*)((const char*)(gbase) + (voff)[_i]), (PG8_LAS unsigned*)(lds + (bufoff) + ldsw + _i * 8192), 16, 0, 0); } while (0)
; #define PG8_LDA(dst, b, h) do { _Pragma("unroll") for (int m = 0; m < 4; ++m) _Pragma("unroll") for (int k = 0; k < 2; ++k) dst[m][k] = *(const PG8_LAS bf16x8*)(lds + PG8_SA(b, h) + aoff + m * 2048 + k * 1024); } while (0)
; #define PG8_LDB(dst, b, h) do { _Pragma("unroll") for (int n = 0; n < 2; ++n) _Pragma("unroll") for (int k = 0; k < 2; ++k) dst[n][k] = *(const PG8_LAS bf16x8*)(lds + PG8_SB(b, h) + boff + n * 2048 + k * 1024); } while (0)
; #define PG8_MMA(ai, bj, At, Bt) do { __builtin_amdgcn_s_setprio(1); _Pragma("unroll") for (int m = 0; m < 4; ++m) _Pragma("unroll") for (int n = 0; n < 2; ++n) _Pragma("unroll") for (int k = 0; k < 2; ++k) \
;         acc[ai][bj][m][n] = __builtin_amdgcn_mfma_f32_16x16x32_bf16(Bt[n][k], At[m][k], acc[ai][bj][m][n], 0, 0, 0); __builtin_amdgcn_s_setprio(0); } while (0)
; #define PG8_WAIT_V(n) asm volatile("s_waitcnt vmcnt(" #n ")" ::: "memory")
; #define PG8_WAIT_L(n) asm volatile("s_waitcnt lgkmcnt(" #n ")" ::: "memory")
; #define PG8_BAR __builtin_amdgcn_s_barrier()
; #define PG8_SCHED __builtin_amdgcn_sched_barrier(0)
; template <class Epi, class Sched, bool ALIGN_EPI = false, bool SP2 = false>
; __device__ __forceinline__ void gemm_phase(PG8_LAS unsigned char* lds, const Gemm g, const Sched& S, const Epi& E) {
;     ...
;             PG8_LDB(B0, 1, 0); PG8_LDB(B1, 1, 1); PG8_SCHED; PG8_LDA(At, 1, 0); PG8_STAGE(PG8_SA(0, 1), a2 + hstep, voffA);
;             PG8_WAIT_V(8); PG8_WAIT_L(0); PG8_BAR; PG8_MMA(0, 0, At, B0); PG8_MMA(0, 1, At, B1); PG8_BAR; PG8_SCHED;
	s_add_i32 s56, 0, 0x18000
	s_add_i32 s57, 0, 0x1c000
	v_add_u32_e32 v94, s56, v203
	v_add_u32_e32 v134, s57, v203
	ds_read_b128 v[66:69], v94
	ds_read_b128 v[70:73], v94 offset:1024
	ds_read_b128 v[82:85], v94 offset:2048
	ds_read_b128 v[94:97], v94 offset:3072
	ds_read_b128 v[106:109], v134
	ds_read_b128 v[118:121], v134 offset:1024
	ds_read_b128 v[130:133], v134 offset:2048
	ds_read_b128 v[134:137], v134 offset:3072
	s_add_u32 s36, s36, 0x40000
	s_addc_u32 s37, s37, 0
	s_mov_b32 m0, s45
	v_lshl_add_u64 v[228:229], s[36:37], 0, v[182:183]
	ds_read_b128 v[162:165], v204 offset:32768
	ds_read_b128 v[166:169], v204 offset:33792
	ds_read_b128 v[188:191], v204 offset:34816
	ds_read_b128 v[192:195], v204 offset:35840
	ds_read_b128 v[196:199], v204 offset:36864
	ds_read_b128 v[206:209], v204 offset:37888
	ds_read_b128 v[210:213], v204 offset:38912
	ds_read_b128 v[214:217], v204 offset:39936
	global_load_lds_dwordx4 v[228:229], off
	v_lshl_add_u64 v[228:229], s[36:37], 0, v[172:173]
	s_mov_b32 m0, s46
	s_nop 0
	global_load_lds_dwordx4 v[228:229], off
	s_waitcnt vmcnt(8)
	s_waitcnt lgkmcnt(0)
	s_barrier
	s_setprio 1
	s_waitcnt lgkmcnt(0)
	v_mfma_f32_16x16x32_bf16 v[158:161], v[66:69], v[162:165], v[158:161]
	v_mfma_f32_16x16x32_bf16 v[154:157], v[82:85], v[162:165], v[154:157]
	v_mfma_f32_16x16x32_bf16 v[142:145], v[66:69], v[188:191], v[142:145]
	v_mfma_f32_16x16x32_bf16 v[138:141], v[82:85], v[188:191], v[138:141]
	v_mfma_f32_16x16x32_bf16 v[114:117], v[66:69], v[196:199], v[114:117]
	v_mfma_f32_16x16x32_bf16 v[110:113], v[82:85], v[196:199], v[110:113]
	v_mfma_f32_16x16x32_bf16 v[90:93], v[66:69], v[210:213], v[90:93]
	v_mfma_f32_16x16x32_bf16 v[86:89], v[82:85], v[210:213], v[86:89]
	v_mfma_f32_16x16x32_bf16 v[158:161], v[70:73], v[166:169], v[158:161]
	v_mfma_f32_16x16x32_bf16 v[154:157], v[94:97], v[166:169], v[154:157]
	v_mfma_f32_16x16x32_bf16 v[142:145], v[70:73], v[192:195], v[142:145]
	v_mfma_f32_16x16x32_bf16 v[138:141], v[94:97], v[192:195], v[138:141]
	v_mfma_f32_16x16x32_bf16 v[114:117], v[70:73], v[206:209], v[114:117]
	v_mfma_f32_16x16x32_bf16 v[110:113], v[94:97], v[206:209], v[110:113]
	v_mfma_f32_16x16x32_bf16 v[90:93], v[70:73], v[214:217], v[90:93]
	v_mfma_f32_16x16x32_bf16 v[86:89], v[94:97], v[214:217], v[86:89]
	v_mfma_f32_16x16x32_bf16 v[150:153], v[106:109], v[162:165], v[150:153]
	v_mfma_f32_16x16x32_bf16 v[146:149], v[130:133], v[162:165], v[146:149]
	v_mfma_f32_16x16x32_bf16 v[126:129], v[106:109], v[188:191], v[126:129]
	v_mfma_f32_16x16x32_bf16 v[122:125], v[130:133], v[188:191], v[122:125]
	v_mfma_f32_16x16x32_bf16 v[102:105], v[106:109], v[196:199], v[102:105]
	v_mfma_f32_16x16x32_bf16 v[98:101], v[130:133], v[196:199], v[98:101]
	v_mfma_f32_16x16x32_bf16 v[78:81], v[106:109], v[210:213], v[78:81]
	v_mfma_f32_16x16x32_bf16 v[74:77], v[130:133], v[210:213], v[74:77]
	v_mfma_f32_16x16x32_bf16 v[150:153], v[118:121], v[166:169], v[150:153]
	v_mfma_f32_16x16x32_bf16 v[146:149], v[134:137], v[166:169], v[146:149]
	v_mfma_f32_16x16x32_bf16 v[126:129], v[118:121], v[192:195], v[126:129]
	v_mfma_f32_16x16x32_bf16 v[122:125], v[134:137], v[192:195], v[122:125]
	v_mfma_f32_16x16x32_bf16 v[102:105], v[118:121], v[206:209], v[102:105]
	v_mfma_f32_16x16x32_bf16 v[98:101], v[134:137], v[206:209], v[98:101]
	v_mfma_f32_16x16x32_bf16 v[78:81], v[118:121], v[214:217], v[78:81]
	v_mfma_f32_16x16x32_bf16 v[74:77], v[134:137], v[214:217], v[74:77]
	s_setprio 0
	s_barrier
; #define PG8_STAGE(bufoff, gbase, voff) do { _Pragma("unroll") for (int _i = 0; _i < 2; ++_i) \
;         __builtin_amdgcn_global_load_lds((const unsigned*)((const char*)(gbase) + (voff)[_i]), (PG8_LAS unsigned*)(lds + (bufoff) + ldsw + _i * 8192), 16, 0, 0); } while (0)
; #define PG8_LDA(dst, b, h) do { _Pragma("unroll") for (int m = 0; m < 4; ++m) _Pragma("unroll") for (int k = 0; k < 2; ++k) dst[m][k] = *(const PG8_LAS bf16x8*)(lds + PG8_SA(b, h) + aoff + m * 2048 + k * 1024); } while (0)
; #define PG8_MMA(ai, bj, At, Bt) do { __builtin_amdgcn_s_setprio(1); _Pragma("unroll") for (int m = 0; m < 4; ++m) _Pragma("unroll") for (int n = 0; n < 2; ++n) _Pragma("unroll") for (int k = 0; k < 2; ++k) \
;         acc[ai][bj][m][n] = __builtin_amdgcn_mfma_f32_16x16x32_bf16(Bt[n][k], At[m][k], acc[ai][bj][m][n], 0, 0, 0); __builtin_amdgcn_s_setprio(0); } while (0)
; #define PG8_WAIT_V(n) asm volatile("s_waitcnt vmcnt(" #n ")" ::: "memory")
; #define PG8_WAIT_L(n) asm volatile("s_waitcnt lgkmcnt(" #n ")" ::: "memory")
; #define PG8_BAR __builtin_amdgcn_s_barrier()
; #define PG8_SCHED __builtin_amdgcn_sched_barrier(0)
; template <class Epi, class Sched, bool ALIGN_EPI = false, bool SP2 = false>
; __device__ __forceinline__ void gemm_phase(PG8_LAS unsigned char* lds, const Gemm g, const Sched& S, const Epi& E) {
;     ...
;         for (int t = 0; t < nt; t += 2) {
;             const bool last = (t == nt - 2);
;             const char* a1 = cA + (size_t)(t + 1) * kstep;
;             const char* a2 = last ? nA : cA + (size_t)(t + 2) * kstep; const char* b2 = last ? nB : cB + (size_t)(t + 2) * kstep;
;             const char* a3 = a2 + kstep; const char* b3 = b2 + kstep;
;     ...
;             PG8_LDA(At, 1, 1); PG8_STAGE(PG8_SB(1, 0), b3, voffB); PG8_STAGE(PG8_SB(1, 1), b3 + hstep, voffB); PG8_STAGE(PG8_SA(1, 0), a3, voffA);
;             PG8_WAIT_V(8); PG8_WAIT_L(0); PG8_BAR; PG8_MMA(1, 0, At, B0); PG8_MMA(1, 1, At, B1); PG8_BAR; PG8_SCHED;
	s_add_i32 s36, s56, s42
	v_lshl_add_u64 v[200:201], v[200:201], 0, s[96:97]
	s_mov_b32 m0, s36
	ds_read_b128 v[162:165], v204 offset:49152
	ds_read_b128 v[166:169], v204 offset:50176
	ds_read_b128 v[188:191], v204 offset:51200
	ds_read_b128 v[192:195], v204 offset:52224
	ds_read_b128 v[196:199], v204 offset:53248
	ds_read_b128 v[206:209], v204 offset:54272
	ds_read_b128 v[210:213], v204 offset:55296
	ds_read_b128 v[214:217], v204 offset:56320
	global_load_lds_dwordx4 v[200:201], off
	s_add_i32 m0, s36, 0x2000
	s_add_u32 s12, s12, 0x40080
	v_lshl_add_u64 v[200:201], v[218:219], 0, s[96:97]
	s_addc_u32 s13, s13, 0
	s_add_i32 s36, s57, s42
	global_load_lds_dwordx4 v[200:201], off
	v_lshl_add_u64 v[200:201], s[12:13], 0, v[180:181]
	s_mov_b32 m0, s36
	s_nop 0
	global_load_lds_dwordx4 v[200:201], off
	v_lshl_add_u64 v[200:201], s[12:13], 0, v[170:171]
	s_add_i32 m0, s36, 0x2000
	s_nop 0
	global_load_lds_dwordx4 v[200:201], off
	v_lshl_add_u64 v[200:201], v[220:221], 0, s[96:97]
	s_mov_b32 m0, s50
	s_nop 0
	global_load_lds_dwordx4 v[200:201], off
	v_lshl_add_u64 v[200:201], v[222:223], 0, s[96:97]
	s_mov_b32 m0, s51
	s_nop 0
	global_load_lds_dwordx4 v[200:201], off
	s_add_i32 s55, s55, 2
	s_add_u32 s10, s10, 0x100
	s_addc_u32 s11, s11, 0
	s_add_u32 s33, s33, 0x100
	s_addc_u32 s54, s54, 0
	s_add_u32 s12, s10, 0xfffc0080
	s_addc_u32 s13, s11, -1
	s_add_i32 s56, 0, 0x10000
	s_cmp_eq_u32 s55, 12
	s_cselect_b32 s37, s5, s13
	s_cselect_b32 s36, s25, s12
	s_cselect_b32 s13, s27, s54
	s_cselect_b32 s12, s29, s33
	s_add_i32 s58, 0, 0x14000
	s_waitcnt vmcnt(8)
	s_waitcnt lgkmcnt(0)
	s_barrier
	s_setprio 1
	s_waitcnt lgkmcnt(0)
	v_mfma_f32_16x16x32_bf16 v[62:65], v[66:69], v[162:165], v[62:65]
	v_mfma_f32_16x16x32_bf16 v[58:61], v[82:85], v[162:165], v[58:61]
	v_mfma_f32_16x16x32_bf16 v[46:49], v[66:69], v[188:191], v[46:49]
	v_mfma_f32_16x16x32_bf16 v[42:45], v[82:85], v[188:191], v[42:45]
	v_mfma_f32_16x16x32_bf16 v[30:33], v[66:69], v[196:199], v[30:33]
	v_mfma_f32_16x16x32_bf16 v[26:29], v[82:85], v[196:199], v[26:29]
	v_mfma_f32_16x16x32_bf16 v[14:17], v[66:69], v[210:213], v[14:17]
	v_mfma_f32_16x16x32_bf16 v[10:13], v[82:85], v[210:213], v[10:13]
	v_mfma_f32_16x16x32_bf16 v[62:65], v[70:73], v[166:169], v[62:65]
	v_mfma_f32_16x16x32_bf16 v[58:61], v[94:97], v[166:169], v[58:61]
	v_mfma_f32_16x16x32_bf16 v[46:49], v[70:73], v[192:195], v[46:49]
	v_mfma_f32_16x16x32_bf16 v[42:45], v[94:97], v[192:195], v[42:45]
	v_mfma_f32_16x16x32_bf16 v[30:33], v[70:73], v[206:209], v[30:33]
	v_mfma_f32_16x16x32_bf16 v[26:29], v[94:97], v[206:209], v[26:29]
	v_mfma_f32_16x16x32_bf16 v[14:17], v[70:73], v[214:217], v[14:17]
	v_mfma_f32_16x16x32_bf16 v[10:13], v[94:97], v[214:217], v[10:13]
	v_mfma_f32_16x16x32_bf16 v[54:57], v[106:109], v[162:165], v[54:57]
	v_mfma_f32_16x16x32_bf16 v[50:53], v[130:133], v[162:165], v[50:53]
	v_mfma_f32_16x16x32_bf16 v[38:41], v[106:109], v[188:191], v[38:41]
	v_mfma_f32_16x16x32_bf16 v[34:37], v[130:133], v[188:191], v[34:37]
	v_mfma_f32_16x16x32_bf16 v[22:25], v[106:109], v[196:199], v[22:25]
	v_mfma_f32_16x16x32_bf16 v[18:21], v[130:133], v[196:199], v[18:21]
	v_mfma_f32_16x16x32_bf16 v[6:9], v[106:109], v[210:213], v[6:9]
	v_mfma_f32_16x16x32_bf16 v[2:5], v[130:133], v[210:213], v[2:5]
	v_mfma_f32_16x16x32_bf16 v[54:57], v[118:121], v[166:169], v[54:57]
	v_mfma_f32_16x16x32_bf16 v[50:53], v[134:137], v[166:169], v[50:53]
	v_mfma_f32_16x16x32_bf16 v[38:41], v[118:121], v[192:195], v[38:41]
	v_mfma_f32_16x16x32_bf16 v[34:37], v[134:137], v[192:195], v[34:37]
	v_mfma_f32_16x16x32_bf16 v[22:25], v[118:121], v[206:209], v[22:25]
	v_mfma_f32_16x16x32_bf16 v[18:21], v[134:137], v[206:209], v[18:21]
	v_mfma_f32_16x16x32_bf16 v[6:9], v[118:121], v[214:217], v[6:9]
	v_mfma_f32_16x16x32_bf16 v[2:5], v[134:137], v[214:217], v[2:5]
	s_setprio 0
	s_barrier
	s_cmp_gt_u32 s55, 13
	s_cbranch_scc0 .Lrot_odout
	s_and_b64 vcc, exec, s[20:21]
	s_cbranch_vccz .LBB0_636
	s_barrier

; #define PG8_STAGE(bufoff, gbase, voff) do { _Pragma("unroll") for (int _i = 0; _i < 2; ++_i) \
;         __builtin_amdgcn_global_load_lds((const unsigned*)((const char*)(gbase) + (voff)[_i]), (PG8_LAS unsigned*)(lds + (bufoff) + ldsw + _i * 8192), 16, 0, 0); } while (0)
; #define PG8_LDA(dst, b, h) do { _Pragma("unroll") for (int m = 0; m < 4; ++m) _Pragma("unroll") for (int k = 0; k < 2; ++k) dst[m][k] = *(const PG8_LAS bf16x8*)(lds + PG8_SA(b, h) + aoff + m * 2048 + k * 1024); } while (0)
; #define PG8_MMA(ai, bj, At, Bt) do { __builtin_amdgcn_s_setprio(1); _Pragma("unroll") for (int m = 0; m < 4; ++m) _Pragma("unroll") for (int n = 0; n < 2; ++n) _Pragma("unroll") for (int k = 0; k < 2; ++k) \
;         acc[ai][bj][m][n] = __builtin_amdgcn_mfma_f32_16x16x32_bf16(Bt[n][k], At[m][k], acc[ai][bj][m][n], 0, 0, 0); __builtin_amdgcn_s_setprio(0); } while (0)
; #define PG8_WAIT_V(n) asm volatile("s_waitcnt vmcnt(" #n ")" ::: "memory")
; #define PG8_WAIT_L(n) asm volatile("s_waitcnt lgkmcnt(" #n ")" ::: "memory")
; #define PG8_BAR __builtin_amdgcn_s_barrier()
; #define PG8_SCHED __builtin_amdgcn_sched_barrier(0)
; template <class Epi, class Sched, bool ALIGN_EPI = false, bool SP2 = false>
; __device__ __forceinline__ void gemm_phase(PG8_LAS unsigned char* lds, const Gemm g, const Sched& S, const Epi& E) {
;     ...
;             PG8_WAIT_V(8); PG8_WAIT_L(0); PG8_BAR; PG8_MMA(0, 0, At, B0); PG8_MMA(0, 1, At, B1); PG8_BAR; PG8_SCHED;
;             PG8_LDA(At, 0, 1); PG8_STAGE(PG8_SB(0, 0), b2, voffB); PG8_STAGE(PG8_SB(0, 1), b2 + hstep, voffB); PG8_STAGE(PG8_SA(0, 0), a2, voffA);
;             PG8_WAIT_V(8); PG8_WAIT_L(0); PG8_BAR; PG8_MMA(1, 0, At, B0); PG8_MMA(1, 1, At, B1); PG8_BAR; PG8_SCHED;
.Levin_noz:
	s_waitcnt vmcnt(8)
	s_waitcnt lgkmcnt(0)
	s_barrier
	s_setprio 1
	s_waitcnt lgkmcnt(0)
	v_mfma_f32_16x16x32_bf16 v[126:129], v[150:153], v[188:191], v[126:129]
	v_mfma_f32_16x16x32_bf16 v[122:125], v[158:161], v[188:191], v[122:125]
	v_mfma_f32_16x16x32_bf16 v[114:117], v[150:153], v[196:199], v[114:117]
	v_mfma_f32_16x16x32_bf16 v[106:109], v[158:161], v[196:199], v[106:109]
	v_mfma_f32_16x16x32_bf16 v[98:101], v[150:153], v[204:207], v[98:101]
	v_mfma_f32_16x16x32_bf16 v[90:93], v[158:161], v[204:207], v[90:93]
	v_mfma_f32_16x16x32_bf16 v[82:85], v[150:153], v[212:215], v[82:85]
	v_mfma_f32_16x16x32_bf16 v[74:77], v[158:161], v[212:215], v[74:77]
	v_mfma_f32_16x16x32_bf16 v[126:129], v[154:157], v[192:195], v[126:129]
	v_mfma_f32_16x16x32_bf16 v[122:125], v[162:165], v[192:195], v[122:125]
	v_mfma_f32_16x16x32_bf16 v[114:117], v[154:157], v[200:203], v[114:117]
	v_mfma_f32_16x16x32_bf16 v[106:109], v[162:165], v[200:203], v[106:109]
	v_mfma_f32_16x16x32_bf16 v[98:101], v[154:157], v[208:211], v[98:101]
	v_mfma_f32_16x16x32_bf16 v[90:93], v[162:165], v[208:211], v[90:93]
	v_mfma_f32_16x16x32_bf16 v[82:85], v[154:157], v[216:219], v[82:85]
	v_mfma_f32_16x16x32_bf16 v[74:77], v[162:165], v[216:219], v[74:77]
	v_mfma_f32_16x16x32_bf16 v[118:121], v[166:169], v[188:191], v[118:121]
	v_mfma_f32_16x16x32_bf16 v[110:113], v[180:183], v[188:191], v[110:113]
	v_mfma_f32_16x16x32_bf16 v[102:105], v[166:169], v[196:199], v[102:105]
	v_mfma_f32_16x16x32_bf16 v[94:97], v[180:183], v[196:199], v[94:97]
	v_mfma_f32_16x16x32_bf16 v[86:89], v[166:169], v[204:207], v[86:89]
	v_mfma_f32_16x16x32_bf16 v[78:81], v[180:183], v[204:207], v[78:81]
	v_mfma_f32_16x16x32_bf16 v[70:73], v[166:169], v[212:215], v[70:73]
	v_mfma_f32_16x16x32_bf16 v[66:69], v[180:183], v[212:215], v[66:69]
	v_mfma_f32_16x16x32_bf16 v[118:121], v[170:173], v[192:195], v[118:121]
	v_mfma_f32_16x16x32_bf16 v[110:113], v[184:187], v[192:195], v[110:113]
	v_mfma_f32_16x16x32_bf16 v[102:105], v[170:173], v[200:203], v[102:105]
	v_mfma_f32_16x16x32_bf16 v[94:97], v[184:187], v[200:203], v[94:97]
	v_mfma_f32_16x16x32_bf16 v[86:89], v[170:173], v[208:211], v[86:89]
	v_mfma_f32_16x16x32_bf16 v[78:81], v[184:187], v[208:211], v[78:81]
	v_mfma_f32_16x16x32_bf16 v[70:73], v[170:173], v[216:219], v[70:73]
	v_mfma_f32_16x16x32_bf16 v[66:69], v[184:187], v[216:219], v[66:69]
	s_setprio 0
	s_barrier
	s_add_i32 s49, s49, s35
	v_lshl_add_u64 v[146:147], s[26:27], 0, v[134:135]
	s_mov_b32 m0, s49
	ds_read_b128 v[188:191], v149 offset:16384
	ds_read_b128 v[192:195], v149 offset:17408
	ds_read_b128 v[196:199], v149 offset:18432
	ds_read_b128 v[200:203], v149 offset:19456
	ds_read_b128 v[204:207], v149 offset:20480
	ds_read_b128 v[208:211], v149 offset:21504
	ds_read_b128 v[212:215], v149 offset:22528
	ds_read_b128 v[216:219], v149 offset:23552
	global_load_lds_dwordx4 v[146:147], off
	s_add_i32 m0, s49, 0x2000
	s_add_u32 s50, s26, 0x40000
	v_lshl_add_u64 v[220:221], s[26:27], 0, v[130:131]
	s_addc_u32 s51, s27, 0
	s_add_i32 s49, s52, s35
	global_load_lds_dwordx4 v[220:221], off
	v_lshl_add_u64 v[222:223], s[50:51], 0, v[134:135]
	s_mov_b32 m0, s49
	v_lshl_add_u64 v[228:229], s[28:29], 0, v[132:133]
	global_load_lds_dwordx4 v[222:223], off
	v_lshl_add_u64 v[222:223], s[50:51], 0, v[130:131]
	s_add_i32 m0, s49, 0x2000
	s_nop 0
	global_load_lds_dwordx4 v[222:223], off
	v_lshl_add_u64 v[222:223], s[28:29], 0, v[136:137]
	s_mov_b32 m0, s36
	s_nop 0
	global_load_lds_dwordx4 v[222:223], off
	s_mov_b32 m0, s37
	s_nop 0
	global_load_lds_dwordx4 v[228:229], off
	s_waitcnt vmcnt(8)
	s_waitcnt lgkmcnt(0)
	s_barrier
	s_setprio 1
	s_waitcnt lgkmcnt(0)
	v_mfma_f32_16x16x32_bf16 v[62:65], v[150:153], v[188:191], v[62:65]
	v_mfma_f32_16x16x32_bf16 v[58:61], v[158:161], v[188:191], v[58:61]
	v_mfma_f32_16x16x32_bf16 v[50:53], v[150:153], v[196:199], v[50:53]
	v_mfma_f32_16x16x32_bf16 v[42:45], v[158:161], v[196:199], v[42:45]
	v_mfma_f32_16x16x32_bf16 v[34:37], v[150:153], v[204:207], v[34:37]
	v_mfma_f32_16x16x32_bf16 v[26:29], v[158:161], v[204:207], v[26:29]
	v_mfma_f32_16x16x32_bf16 v[18:21], v[150:153], v[212:215], v[18:21]
	v_mfma_f32_16x16x32_bf16 v[10:13], v[158:161], v[212:215], v[10:13]
	v_mfma_f32_16x16x32_bf16 v[62:65], v[154:157], v[192:195], v[62:65]
	v_mfma_f32_16x16x32_bf16 v[58:61], v[162:165], v[192:195], v[58:61]
	v_mfma_f32_16x16x32_bf16 v[50:53], v[154:157], v[200:203], v[50:53]
	v_mfma_f32_16x16x32_bf16 v[42:45], v[162:165], v[200:203], v[42:45]
	v_mfma_f32_16x16x32_bf16 v[34:37], v[154:157], v[208:211], v[34:37]
	v_mfma_f32_16x16x32_bf16 v[26:29], v[162:165], v[208:211], v[26:29]
	v_mfma_f32_16x16x32_bf16 v[18:21], v[154:157], v[216:219], v[18:21]
	v_mfma_f32_16x16x32_bf16 v[10:13], v[162:165], v[216:219], v[10:13]
	v_mfma_f32_16x16x32_bf16 v[54:57], v[166:169], v[188:191], v[54:57]
	v_mfma_f32_16x16x32_bf16 v[46:49], v[180:183], v[188:191], v[46:49]
	v_mfma_f32_16x16x32_bf16 v[38:41], v[166:169], v[196:199], v[38:41]
	v_mfma_f32_16x16x32_bf16 v[30:33], v[180:183], v[196:199], v[30:33]
	v_mfma_f32_16x16x32_bf16 v[22:25], v[166:169], v[204:207], v[22:25]
	v_mfma_f32_16x16x32_bf16 v[14:17], v[180:183], v[204:207], v[14:17]
	v_mfma_f32_16x16x32_bf16 v[6:9], v[166:169], v[212:215], v[6:9]
	v_mfma_f32_16x16x32_bf16 v[2:5], v[180:183], v[212:215], v[2:5]
	v_mfma_f32_16x16x32_bf16 v[54:57], v[170:173], v[192:195], v[54:57]
	v_mfma_f32_16x16x32_bf16 v[46:49], v[184:187], v[192:195], v[46:49]
	v_mfma_f32_16x16x32_bf16 v[38:41], v[170:173], v[200:203], v[38:41]
	v_mfma_f32_16x16x32_bf16 v[30:33], v[184:187], v[200:203], v[30:33]
	v_mfma_f32_16x16x32_bf16 v[22:25], v[170:173], v[208:211], v[22:25]
	v_mfma_f32_16x16x32_bf16 v[14:17], v[184:187], v[208:211], v[14:17]
	v_mfma_f32_16x16x32_bf16 v[6:9], v[170:173], v[216:219], v[6:9]
	v_mfma_f32_16x16x32_bf16 v[2:5], v[184:187], v[216:219], v[2:5]
	s_setprio 0
	s_barrier
; #define PG8_STAGE(bufoff, gbase, voff) do { _Pragma("unroll") for (int _i = 0; _i < 2; ++_i) \
;         __builtin_amdgcn_global_load_lds((const unsigned*)((const char*)(gbase) + (voff)[_i]), (PG8_LAS unsigned*)(lds + (bufoff) + ldsw + _i * 8192), 16, 0, 0); } while (0)
; #define PG8_LDA(dst, b, h) do { _Pragma("unroll") for (int m = 0; m < 4; ++m) _Pragma("unroll") for (int k = 0; k < 2; ++k) dst[m][k] = *(const PG8_LAS bf16x8*)(lds + PG8_SA(b, h) + aoff + m * 2048 + k * 1024); } while (0)
; #define PG8_LDB(dst, b, h) do { _Pragma("unroll") for (int n = 0; n < 2; ++n) _Pragma("unroll") for (int k = 0; k < 2; ++k) dst[n][k] = *(const PG8_LAS bf16x8*)(lds + PG8_SB(b, h) + boff + n * 2048 + k * 1024); } while (0)
; #define PG8_MMA(ai, bj, At, Bt) do { __builtin_amdgcn_s_setprio(1); _Pragma("unroll") for (int m = 0; m < 4; ++m) _Pragma("unroll") for (int n = 0; n < 2; ++n) _Pragma("unroll") for (int k = 0; k < 2; ++k) \
;         acc[ai][bj][m][n] = __builtin_amdgcn_mfma_f32_16x16x32_bf16(Bt[n][k], At[m][k], acc[ai][bj][m][n], 0, 0, 0); __builtin_amdgcn_s_setprio(0); } while (0)
; #define PG8_WAIT_V(n) asm volatile("s_waitcnt vmcnt(" #n ")" ::: "memory")
; #define PG8_WAIT_L(n) asm volatile("s_waitcnt lgkmcnt(" #n ")" ::: "memory")
; #define PG8_BAR __builtin_amdgcn_s_barrier()
; #define PG8_SCHED __builtin_amdgcn_sched_barrier(0)
; template <class Epi, class Sched, bool ALIGN_EPI = false, bool SP2 = false>
; __device__ __forceinline__ void gemm_phase(PG8_LAS unsigned char* lds, const Gemm g, const Sched& S, const Epi& E) {
;     ...
;             PG8_LDB(B0, 1, 0); PG8_LDB(B1, 1, 1); PG8_SCHED; PG8_LDA(At, 1, 0); PG8_STAGE(PG8_SA(0, 1), a2 + hstep, voffA);
;             PG8_WAIT_V(8); PG8_WAIT_L(0); PG8_BAR; PG8_MMA(0, 0, At, B0); PG8_MMA(0, 1, At, B1); PG8_BAR; PG8_SCHED;
	s_add_i32 s49, 0, 0x18000
	v_add_u32_e32 v142, s49, v145
	s_add_i32 s50, 0, 0x1c000
	ds_read_b128 v[150:153], v142
	ds_read_b128 v[154:157], v142 offset:1024
	ds_read_b128 v[158:161], v142 offset:2048
	ds_read_b128 v[162:165], v142 offset:3072
	v_add_u32_e32 v142, s50, v145
	ds_read_b128 v[166:169], v142
	ds_read_b128 v[170:173], v142 offset:1024
	ds_read_b128 v[180:183], v142 offset:2048
	ds_read_b128 v[184:187], v142 offset:3072
	s_add_u32 s28, s28, 0x40000
	s_addc_u32 s29, s29, 0
	s_mov_b32 m0, s38
	v_lshl_add_u64 v[230:231], s[28:29], 0, v[136:137]
	ds_read_b128 v[188:191], v149 offset:32768
	ds_read_b128 v[192:195], v149 offset:33792
	ds_read_b128 v[196:199], v149 offset:34816
	ds_read_b128 v[200:203], v149 offset:35840
	ds_read_b128 v[204:207], v149 offset:36864
	ds_read_b128 v[208:211], v149 offset:37888
	ds_read_b128 v[212:215], v149 offset:38912
	ds_read_b128 v[216:219], v149 offset:39936
	global_load_lds_dwordx4 v[230:231], off
	v_lshl_add_u64 v[230:231], s[28:29], 0, v[132:133]
	s_mov_b32 m0, s39
	s_nop 0
	global_load_lds_dwordx4 v[230:231], off
	s_waitcnt vmcnt(8)
	s_waitcnt lgkmcnt(0)
	s_barrier
	s_setprio 1
	s_waitcnt lgkmcnt(0)
	v_mfma_f32_16x16x32_bf16 v[126:129], v[150:153], v[188:191], v[126:129]
	v_mfma_f32_16x16x32_bf16 v[122:125], v[158:161], v[188:191], v[122:125]
	v_mfma_f32_16x16x32_bf16 v[114:117], v[150:153], v[196:199], v[114:117]
	v_mfma_f32_16x16x32_bf16 v[106:109], v[158:161], v[196:199], v[106:109]
	v_mfma_f32_16x16x32_bf16 v[98:101], v[150:153], v[204:207], v[98:101]
	v_mfma_f32_16x16x32_bf16 v[90:93], v[158:161], v[204:207], v[90:93]
	v_mfma_f32_16x16x32_bf16 v[82:85], v[150:153], v[212:215], v[82:85]
	v_mfma_f32_16x16x32_bf16 v[74:77], v[158:161], v[212:215], v[74:77]
	v_mfma_f32_16x16x32_bf16 v[126:129], v[154:157], v[192:195], v[126:129]
	v_mfma_f32_16x16x32_bf16 v[122:125], v[162:165], v[192:195], v[122:125]
	v_mfma_f32_16x16x32_bf16 v[114:117], v[154:157], v[200:203], v[114:117]
	v_mfma_f32_16x16x32_bf16 v[106:109], v[162:165], v[200:203], v[106:109]
	v_mfma_f32_16x16x32_bf16 v[98:101], v[154:157], v[208:211], v[98:101]
	v_mfma_f32_16x16x32_bf16 v[90:93], v[162:165], v[208:211], v[90:93]
	v_mfma_f32_16x16x32_bf16 v[82:85], v[154:157], v[216:219], v[82:85]
	v_mfma_f32_16x16x32_bf16 v[74:77], v[162:165], v[216:219], v[74:77]
	v_mfma_f32_16x16x32_bf16 v[118:121], v[166:169], v[188:191], v[118:121]
	v_mfma_f32_16x16x32_bf16 v[110:113], v[180:183], v[188:191], v[110:113]
	v_mfma_f32_16x16x32_bf16 v[102:105], v[166:169], v[196:199], v[102:105]
	v_mfma_f32_16x16x32_bf16 v[94:97], v[180:183], v[196:199], v[94:97]
	v_mfma_f32_16x16x32_bf16 v[86:89], v[166:169], v[204:207], v[86:89]
	v_mfma_f32_16x16x32_bf16 v[78:81], v[180:183], v[204:207], v[78:81]
	v_mfma_f32_16x16x32_bf16 v[70:73], v[166:169], v[212:215], v[70:73]
	v_mfma_f32_16x16x32_bf16 v[66:69], v[180:183], v[212:215], v[66:69]
	v_mfma_f32_16x16x32_bf16 v[118:121], v[170:173], v[192:195], v[118:121]
	v_mfma_f32_16x16x32_bf16 v[110:113], v[184:187], v[192:195], v[110:113]
	v_mfma_f32_16x16x32_bf16 v[102:105], v[170:173], v[200:203], v[102:105]
	v_mfma_f32_16x16x32_bf16 v[94:97], v[184:187], v[200:203], v[94:97]
	v_mfma_f32_16x16x32_bf16 v[86:89], v[170:173], v[208:211], v[86:89]
	v_mfma_f32_16x16x32_bf16 v[78:81], v[184:187], v[208:211], v[78:81]
	v_mfma_f32_16x16x32_bf16 v[70:73], v[170:173], v[216:219], v[70:73]
	v_mfma_f32_16x16x32_bf16 v[66:69], v[184:187], v[216:219], v[66:69]
	s_setprio 0
	s_barrier
; #define PG8_STAGE(bufoff, gbase, voff) do { _Pragma("unroll") for (int _i = 0; _i < 2; ++_i) \
;         __builtin_amdgcn_global_load_lds((const unsigned*)((const char*)(gbase) + (voff)[_i]), (PG8_LAS unsigned*)(lds + (bufoff) + ldsw + _i * 8192), 16, 0, 0); } while (0)
; #define PG8_LDA(dst, b, h) do { _Pragma("unroll") for (int m = 0; m < 4; ++m) _Pragma("unroll") for (int k = 0; k < 2; ++k) dst[m][k] = *(const PG8_LAS bf16x8*)(lds + PG8_SA(b, h) + aoff + m * 2048 + k * 1024); } while (0)
; #define PG8_MMA(ai, bj, At, Bt) do { __builtin_amdgcn_s_setprio(1); _Pragma("unroll") for (int m = 0; m < 4; ++m) _Pragma("unroll") for (int n = 0; n < 2; ++n) _Pragma("unroll") for (int k = 0; k < 2; ++k) \
;         acc[ai][bj][m][n] = __builtin_amdgcn_mfma_f32_16x16x32_bf16(Bt[n][k], At[m][k], acc[ai][bj][m][n], 0, 0, 0); __builtin_amdgcn_s_setprio(0); } while (0)
; #define PG8_WAIT_V(n) asm volatile("s_waitcnt vmcnt(" #n ")" ::: "memory")
; #define PG8_WAIT_L(n) asm volatile("s_waitcnt lgkmcnt(" #n ")" ::: "memory")
; #define PG8_BAR __builtin_amdgcn_s_barrier()
; #define PG8_SCHED __builtin_amdgcn_sched_barrier(0)
; template <class Epi, class Sched, bool ALIGN_EPI = false, bool SP2 = false>
; __device__ __forceinline__ void gemm_phase(PG8_LAS unsigned char* lds, const Gemm g, const Sched& S, const Epi& E) {
;     ...
;         for (int t = 0; t < nt; t += 2) {
;             const bool last = (t == nt - 2);
;             const char* a1 = cA + (size_t)(t + 1) * kstep;
;             const char* a2 = last ? nA : cA + (size_t)(t + 2) * kstep; const char* b2 = last ? nB : cB + (size_t)(t + 2) * kstep;
;             const char* a3 = a2 + kstep; const char* b3 = b2 + kstep;
;     ...
;             PG8_LDA(At, 1, 1); PG8_STAGE(PG8_SB(1, 0), b3, voffB); PG8_STAGE(PG8_SB(1, 1), b3 + hstep, voffB); PG8_STAGE(PG8_SA(1, 0), a3, voffA);
;             PG8_WAIT_V(8); PG8_WAIT_L(0); PG8_BAR; PG8_MMA(1, 0, At, B0); PG8_MMA(1, 1, At, B1); PG8_BAR; PG8_SCHED;
	s_add_i32 s28, s49, s35
	v_lshl_add_u64 v[146:147], v[146:147], 0, s[96:97]
	s_mov_b32 m0, s28
	ds_read_b128 v[188:191], v149 offset:49152
	ds_read_b128 v[192:195], v149 offset:50176
	ds_read_b128 v[196:199], v149 offset:51200
	ds_read_b128 v[200:203], v149 offset:52224
	ds_read_b128 v[204:207], v149 offset:53248
	ds_read_b128 v[208:211], v149 offset:54272
	ds_read_b128 v[212:215], v149 offset:55296
	ds_read_b128 v[216:219], v149 offset:56320
	global_load_lds_dwordx4 v[146:147], off
	s_add_i32 m0, s28, 0x2000
	s_add_u32 s26, s26, 0x40080
	v_lshl_add_u64 v[146:147], v[220:221], 0, s[96:97]
	s_addc_u32 s27, s27, 0
	s_add_i32 s28, s50, s35
	global_load_lds_dwordx4 v[146:147], off
	v_lshl_add_u64 v[146:147], s[26:27], 0, v[134:135]
	s_mov_b32 m0, s28
	s_nop 0
	global_load_lds_dwordx4 v[146:147], off
	v_lshl_add_u64 v[146:147], s[26:27], 0, v[130:131]
	s_add_i32 m0, s28, 0x2000
	s_nop 0
	global_load_lds_dwordx4 v[146:147], off
	v_lshl_add_u64 v[146:147], v[222:223], 0, s[96:97]
	s_mov_b32 m0, s42
	s_nop 0
	global_load_lds_dwordx4 v[146:147], off
	v_lshl_add_u64 v[146:147], v[228:229], 0, s[96:97]
	s_mov_b32 m0, s43
	s_nop 0
	global_load_lds_dwordx4 v[146:147], off
	s_add_i32 s48, s48, 2
	s_add_u32 s24, s24, 0x100
	s_addc_u32 s25, s25, 0
	s_add_u32 s46, s46, 0x100
	s_addc_u32 s47, s47, 0
	s_add_u32 s26, s24, 0xfffc0080
	s_addc_u32 s27, s25, -1
	s_add_i32 s49, 0, 0x10000
	s_cmp_eq_u32 s48, 12
	s_cselect_b32 s29, s19, s27
	s_cselect_b32 s28, s33, s26
	s_cselect_b32 s27, s17, s47
	s_cselect_b32 s26, s45, s46
	s_add_i32 s52, 0, 0x14000
	s_waitcnt vmcnt(8)
	s_waitcnt lgkmcnt(0)
	s_barrier
	s_setprio 1
	s_waitcnt lgkmcnt(0)
	v_mfma_f32_16x16x32_bf16 v[62:65], v[150:153], v[188:191], v[62:65]
	v_mfma_f32_16x16x32_bf16 v[58:61], v[158:161], v[188:191], v[58:61]
	v_mfma_f32_16x16x32_bf16 v[50:53], v[150:153], v[196:199], v[50:53]
	v_mfma_f32_16x16x32_bf16 v[42:45], v[158:161], v[196:199], v[42:45]
	v_mfma_f32_16x16x32_bf16 v[34:37], v[150:153], v[204:207], v[34:37]
	v_mfma_f32_16x16x32_bf16 v[26:29], v[158:161], v[204:207], v[26:29]
	v_mfma_f32_16x16x32_bf16 v[18:21], v[150:153], v[212:215], v[18:21]
	v_mfma_f32_16x16x32_bf16 v[10:13], v[158:161], v[212:215], v[10:13]
	v_mfma_f32_16x16x32_bf16 v[62:65], v[154:157], v[192:195], v[62:65]
	v_mfma_f32_16x16x32_bf16 v[58:61], v[162:165], v[192:195], v[58:61]
	v_mfma_f32_16x16x32_bf16 v[50:53], v[154:157], v[200:203], v[50:53]
	v_mfma_f32_16x16x32_bf16 v[42:45], v[162:165], v[200:203], v[42:45]
	v_mfma_f32_16x16x32_bf16 v[34:37], v[154:157], v[208:211], v[34:37]
	v_mfma_f32_16x16x32_bf16 v[26:29], v[162:165], v[208:211], v[26:29]
	v_mfma_f32_16x16x32_bf16 v[18:21], v[154:157], v[216:219], v[18:21]
	v_mfma_f32_16x16x32_bf16 v[10:13], v[162:165], v[216:219], v[10:13]
	v_mfma_f32_16x16x32_bf16 v[54:57], v[166:169], v[188:191], v[54:57]
	v_mfma_f32_16x16x32_bf16 v[46:49], v[180:183], v[188:191], v[46:49]
	v_mfma_f32_16x16x32_bf16 v[38:41], v[166:169], v[196:199], v[38:41]
	v_mfma_f32_16x16x32_bf16 v[30:33], v[180:183], v[196:199], v[30:33]
	v_mfma_f32_16x16x32_bf16 v[22:25], v[166:169], v[204:207], v[22:25]
	v_mfma_f32_16x16x32_bf16 v[14:17], v[180:183], v[204:207], v[14:17]
	v_mfma_f32_16x16x32_bf16 v[6:9], v[166:169], v[212:215], v[6:9]
	v_mfma_f32_16x16x32_bf16 v[2:5], v[180:183], v[212:215], v[2:5]
	v_mfma_f32_16x16x32_bf16 v[54:57], v[170:173], v[192:195], v[54:57]
	v_mfma_f32_16x16x32_bf16 v[46:49], v[184:187], v[192:195], v[46:49]
	v_mfma_f32_16x16x32_bf16 v[38:41], v[170:173], v[200:203], v[38:41]
	v_mfma_f32_16x16x32_bf16 v[30:33], v[184:187], v[200:203], v[30:33]
	v_mfma_f32_16x16x32_bf16 v[22:25], v[170:173], v[208:211], v[22:25]
	v_mfma_f32_16x16x32_bf16 v[14:17], v[184:187], v[208:211], v[14:17]
	v_mfma_f32_16x16x32_bf16 v[6:9], v[170:173], v[216:219], v[6:9]
	v_mfma_f32_16x16x32_bf16 v[2:5], v[184:187], v[216:219], v[2:5]
	s_setprio 0
	s_barrier
	s_cmp_gt_u32 s48, 13
	s_cbranch_scc0 .Lrot_evin
	s_and_b64 vcc, exec, s[14:15]
	s_cbranch_vccz .LBB0_815
	s_barrier

; #define PG8_STAGE(bufoff, gbase, voff) do { _Pragma("unroll") for (int _i = 0; _i < 2; ++_i) \
;         __builtin_amdgcn_global_load_lds((const unsigned*)((const char*)(gbase) + (voff)[_i]), (PG8_LAS unsigned*)(lds + (bufoff) + ldsw + _i * 8192), 16, 0, 0); } while (0)
; #define PG8_LDA(dst, b, h) do { _Pragma("unroll") for (int m = 0; m < 4; ++m) _Pragma("unroll") for (int k = 0; k < 2; ++k) dst[m][k] = *(const PG8_LAS bf16x8*)(lds + PG8_SA(b, h) + aoff + m * 2048 + k * 1024); } while (0)
; #define PG8_MMA(ai, bj, At, Bt) do { __builtin_amdgcn_s_setprio(1); _Pragma("unroll") for (int m = 0; m < 4; ++m) _Pragma("unroll") for (int n = 0; n < 2; ++n) _Pragma("unroll") for (int k = 0; k < 2; ++k) \
;         acc[ai][bj][m][n] = __builtin_amdgcn_mfma_f32_16x16x32_bf16(Bt[n][k], At[m][k], acc[ai][bj][m][n], 0, 0, 0); __builtin_amdgcn_s_setprio(0); } while (0)
; #define PG8_WAIT_V(n) asm volatile("s_waitcnt vmcnt(" #n ")" ::: "memory")
; #define PG8_WAIT_L(n) asm volatile("s_waitcnt lgkmcnt(" #n ")" ::: "memory")
; #define PG8_BAR __builtin_amdgcn_s_barrier()
; #define PG8_SCHED __builtin_amdgcn_sched_barrier(0)
; template <class Epi, class Sched, bool ALIGN_EPI = false, bool SP2 = false>
; __device__ __forceinline__ void gemm_phase(PG8_LAS unsigned char* lds, const Gemm g, const Sched& S, const Epi& E) {
;     ...
;             PG8_WAIT_V(8); PG8_WAIT_L(0); PG8_BAR; PG8_MMA(0, 0, At, B0); PG8_MMA(0, 1, At, B1); PG8_BAR; PG8_SCHED;
;             PG8_LDA(At, 0, 1); PG8_STAGE(PG8_SB(0, 0), b2, voffB); PG8_STAGE(PG8_SB(0, 1), b2 + hstep, voffB); PG8_STAGE(PG8_SA(0, 0), a2, voffA);
;             PG8_WAIT_V(8); PG8_WAIT_L(0); PG8_BAR; PG8_MMA(1, 0, At, B0); PG8_MMA(1, 1, At, B1); PG8_BAR; PG8_SCHED;
.Levout_noz:
	s_waitcnt vmcnt(8)
	s_waitcnt lgkmcnt(0)
	s_barrier
	s_setprio 1
	s_waitcnt lgkmcnt(0)
	v_mfma_f32_16x16x32_bf16 v[158:161], v[66:69], v[162:165], v[158:161]
	v_mfma_f32_16x16x32_bf16 v[154:157], v[82:85], v[162:165], v[154:157]
	v_mfma_f32_16x16x32_bf16 v[142:145], v[66:69], v[188:191], v[142:145]
	v_mfma_f32_16x16x32_bf16 v[138:141], v[82:85], v[188:191], v[138:141]
	v_mfma_f32_16x16x32_bf16 v[114:117], v[66:69], v[196:199], v[114:117]
	v_mfma_f32_16x16x32_bf16 v[110:113], v[82:85], v[196:199], v[110:113]
	v_mfma_f32_16x16x32_bf16 v[90:93], v[66:69], v[210:213], v[90:93]
	v_mfma_f32_16x16x32_bf16 v[86:89], v[82:85], v[210:213], v[86:89]
	v_mfma_f32_16x16x32_bf16 v[158:161], v[70:73], v[166:169], v[158:161]
	v_mfma_f32_16x16x32_bf16 v[154:157], v[94:97], v[166:169], v[154:157]
	v_mfma_f32_16x16x32_bf16 v[142:145], v[70:73], v[192:195], v[142:145]
	v_mfma_f32_16x16x32_bf16 v[138:141], v[94:97], v[192:195], v[138:141]
	v_mfma_f32_16x16x32_bf16 v[114:117], v[70:73], v[206:209], v[114:117]
	v_mfma_f32_16x16x32_bf16 v[110:113], v[94:97], v[206:209], v[110:113]
	v_mfma_f32_16x16x32_bf16 v[90:93], v[70:73], v[214:217], v[90:93]
	v_mfma_f32_16x16x32_bf16 v[86:89], v[94:97], v[214:217], v[86:89]
	v_mfma_f32_16x16x32_bf16 v[150:153], v[106:109], v[162:165], v[150:153]
	v_mfma_f32_16x16x32_bf16 v[146:149], v[130:133], v[162:165], v[146:149]
	v_mfma_f32_16x16x32_bf16 v[126:129], v[106:109], v[188:191], v[126:129]
	v_mfma_f32_16x16x32_bf16 v[122:125], v[130:133], v[188:191], v[122:125]
	v_mfma_f32_16x16x32_bf16 v[102:105], v[106:109], v[196:199], v[102:105]
	v_mfma_f32_16x16x32_bf16 v[98:101], v[130:133], v[196:199], v[98:101]
	v_mfma_f32_16x16x32_bf16 v[78:81], v[106:109], v[210:213], v[78:81]
	v_mfma_f32_16x16x32_bf16 v[74:77], v[130:133], v[210:213], v[74:77]
	v_mfma_f32_16x16x32_bf16 v[150:153], v[118:121], v[166:169], v[150:153]
	v_mfma_f32_16x16x32_bf16 v[146:149], v[134:137], v[166:169], v[146:149]
	v_mfma_f32_16x16x32_bf16 v[126:129], v[118:121], v[192:195], v[126:129]
	v_mfma_f32_16x16x32_bf16 v[122:125], v[134:137], v[192:195], v[122:125]
	v_mfma_f32_16x16x32_bf16 v[102:105], v[118:121], v[206:209], v[102:105]
	v_mfma_f32_16x16x32_bf16 v[98:101], v[134:137], v[206:209], v[98:101]
	v_mfma_f32_16x16x32_bf16 v[78:81], v[118:121], v[214:217], v[78:81]
	v_mfma_f32_16x16x32_bf16 v[74:77], v[134:137], v[214:217], v[74:77]
	s_setprio 0
	s_barrier
	s_add_i32 s56, s56, s42
	v_lshl_add_u64 v[200:201], s[10:11], 0, v[180:181]
	s_mov_b32 m0, s56
	ds_read_b128 v[162:165], v204 offset:16384
	ds_read_b128 v[166:169], v204 offset:17408
	ds_read_b128 v[188:191], v204 offset:18432
	ds_read_b128 v[192:195], v204 offset:19456
	ds_read_b128 v[196:199], v204 offset:20480
	ds_read_b128 v[206:209], v204 offset:21504
	ds_read_b128 v[210:213], v204 offset:22528
	ds_read_b128 v[214:217], v204 offset:23552
	global_load_lds_dwordx4 v[200:201], off
	s_add_i32 m0, s56, 0x2000
	s_add_u32 s56, s10, 0x40000
	v_lshl_add_u64 v[218:219], s[10:11], 0, v[170:171]
	s_addc_u32 s57, s11, 0
	s_add_i32 s58, s58, s42
	global_load_lds_dwordx4 v[218:219], off
	v_lshl_add_u64 v[220:221], s[56:57], 0, v[180:181]
	s_mov_b32 m0, s58
	v_lshl_add_u64 v[222:223], s[36:37], 0, v[172:173]
	global_load_lds_dwordx4 v[220:221], off
	v_lshl_add_u64 v[220:221], s[56:57], 0, v[170:171]
	s_add_i32 m0, s58, 0x2000
	s_nop 0
	global_load_lds_dwordx4 v[220:221], off
	v_lshl_add_u64 v[220:221], s[36:37], 0, v[182:183]
	s_mov_b32 m0, s43
	s_nop 0
	global_load_lds_dwordx4 v[220:221], off
	s_mov_b32 m0, s44
	s_nop 0
	global_load_lds_dwordx4 v[222:223], off
	s_waitcnt vmcnt(8)
	s_waitcnt lgkmcnt(0)
	s_barrier
	s_setprio 1
	s_waitcnt lgkmcnt(0)
	v_mfma_f32_16x16x32_bf16 v[62:65], v[66:69], v[162:165], v[62:65]
	v_mfma_f32_16x16x32_bf16 v[58:61], v[82:85], v[162:165], v[58:61]
	v_mfma_f32_16x16x32_bf16 v[46:49], v[66:69], v[188:191], v[46:49]
	v_mfma_f32_16x16x32_bf16 v[42:45], v[82:85], v[188:191], v[42:45]
	v_mfma_f32_16x16x32_bf16 v[30:33], v[66:69], v[196:199], v[30:33]
	v_mfma_f32_16x16x32_bf16 v[26:29], v[82:85], v[196:199], v[26:29]
	v_mfma_f32_16x16x32_bf16 v[14:17], v[66:69], v[210:213], v[14:17]
	v_mfma_f32_16x16x32_bf16 v[10:13], v[82:85], v[210:213], v[10:13]
	v_mfma_f32_16x16x32_bf16 v[62:65], v[70:73], v[166:169], v[62:65]
	v_mfma_f32_16x16x32_bf16 v[58:61], v[94:97], v[166:169], v[58:61]
	v_mfma_f32_16x16x32_bf16 v[46:49], v[70:73], v[192:195], v[46:49]
	v_mfma_f32_16x16x32_bf16 v[42:45], v[94:97], v[192:195], v[42:45]
	v_mfma_f32_16x16x32_bf16 v[30:33], v[70:73], v[206:209], v[30:33]
	v_mfma_f32_16x16x32_bf16 v[26:29], v[94:97], v[206:209], v[26:29]
	v_mfma_f32_16x16x32_bf16 v[14:17], v[70:73], v[214:217], v[14:17]
	v_mfma_f32_16x16x32_bf16 v[10:13], v[94:97], v[214:217], v[10:13]
	v_mfma_f32_16x16x32_bf16 v[54:57], v[106:109], v[162:165], v[54:57]
	v_mfma_f32_16x16x32_bf16 v[50:53], v[130:133], v[162:165], v[50:53]
	v_mfma_f32_16x16x32_bf16 v[38:41], v[106:109], v[188:191], v[38:41]
	v_mfma_f32_16x16x32_bf16 v[34:37], v[130:133], v[188:191], v[34:37]
	v_mfma_f32_16x16x32_bf16 v[22:25], v[106:109], v[196:199], v[22:25]
	v_mfma_f32_16x16x32_bf16 v[18:21], v[130:133], v[196:199], v[18:21]
	v_mfma_f32_16x16x32_bf16 v[6:9], v[106:109], v[210:213], v[6:9]
	v_mfma_f32_16x16x32_bf16 v[2:5], v[130:133], v[210:213], v[2:5]
	v_mfma_f32_16x16x32_bf16 v[54:57], v[118:121], v[166:169], v[54:57]
	v_mfma_f32_16x16x32_bf16 v[50:53], v[134:137], v[166:169], v[50:53]
	v_mfma_f32_16x16x32_bf16 v[38:41], v[118:121], v[192:195], v[38:41]
	v_mfma_f32_16x16x32_bf16 v[34:37], v[134:137], v[192:195], v[34:37]
	v_mfma_f32_16x16x32_bf16 v[22:25], v[118:121], v[206:209], v[22:25]
	v_mfma_f32_16x16x32_bf16 v[18:21], v[134:137], v[206:209], v[18:21]
	v_mfma_f32_16x16x32_bf16 v[6:9], v[118:121], v[214:217], v[6:9]
	v_mfma_f32_16x16x32_bf16 v[2:5], v[134:137], v[214:217], v[2:5]
	s_setprio 0
	s_barrier
; #define PG8_STAGE(bufoff, gbase, voff) do { _Pragma("unroll") for (int _i = 0; _i < 2; ++_i) \
;         __builtin_amdgcn_global_load_lds((const unsigned*)((const char*)(gbase) + (voff)[_i]), (PG8_LAS unsigned*)(lds + (bufoff) + ldsw + _i * 8192), 16, 0, 0); } while (0)
; #define PG8_LDA(dst, b, h) do { _Pragma("unroll") for (int m = 0; m < 4; ++m) _Pragma("unroll") for (int k = 0; k < 2; ++k) dst[m][k] = *(const PG8_LAS bf16x8*)(lds + PG8_SA(b, h) + aoff + m * 2048 + k * 1024); } while (0)
; #define PG8_LDB(dst, b, h) do { _Pragma("unroll") for (int n = 0; n < 2; ++n) _Pragma("unroll") for (int k = 0; k < 2; ++k) dst[n][k] = *(const PG8_LAS bf16x8*)(lds + PG8_SB(b, h) + boff + n * 2048 + k * 1024); } while (0)
; #define PG8_MMA(ai, bj, At, Bt) do { __builtin_amdgcn_s_setprio(1); _Pragma("unroll") for (int m = 0; m < 4; ++m) _Pragma("unroll") for (int n = 0; n < 2; ++n) _Pragma("unroll") for (int k = 0; k < 2; ++k) \
;         acc[ai][bj][m][n] = __builtin_amdgcn_mfma_f32_16x16x32_bf16(Bt[n][k], At[m][k], acc[ai][bj][m][n], 0, 0, 0); __builtin_amdgcn_s_setprio(0); } while (0)
; #define PG8_WAIT_V(n) asm volatile("s_waitcnt vmcnt(" #n ")" ::: "memory")
; #define PG8_WAIT_L(n) asm volatile("s_waitcnt lgkmcnt(" #n ")" ::: "memory")
; #define PG8_BAR __builtin_amdgcn_s_barrier()
; #define PG8_SCHED __builtin_amdgcn_sched_barrier(0)
; template <class Epi, class Sched, bool ALIGN_EPI = false, bool SP2 = false>
; __device__ __forceinline__ void gemm_phase(PG8_LAS unsigned char* lds, const Gemm g, const Sched& S, const Epi& E) {
;     ...
;             PG8_LDB(B0, 1, 0); PG8_LDB(B1, 1, 1); PG8_SCHED; PG8_LDA(At, 1, 0); PG8_STAGE(PG8_SA(0, 1), a2 + hstep, voffA);
;             PG8_WAIT_V(8); PG8_WAIT_L(0); PG8_BAR; PG8_MMA(0, 0, At, B0); PG8_MMA(0, 1, At, B1); PG8_BAR; PG8_SCHED;
	s_add_i32 s56, 0, 0x18000
	s_add_i32 s57, 0, 0x1c000
	v_add_u32_e32 v94, s56, v203
	v_add_u32_e32 v134, s57, v203
	ds_read_b128 v[66:69], v94
	ds_read_b128 v[70:73], v94 offset:1024
	ds_read_b128 v[82:85], v94 offset:2048
	ds_read_b128 v[94:97], v94 offset:3072
	ds_read_b128 v[106:109], v134
	ds_read_b128 v[118:121], v134 offset:1024
	ds_read_b128 v[130:133], v134 offset:2048
	ds_read_b128 v[134:137], v134 offset:3072
	s_add_u32 s36, s36, 0x40000
	s_addc_u32 s37, s37, 0
	s_mov_b32 m0, s45
	v_lshl_add_u64 v[228:229], s[36:37], 0, v[182:183]
	ds_read_b128 v[162:165], v204 offset:32768
	ds_read_b128 v[166:169], v204 offset:33792
	ds_read_b128 v[188:191], v204 offset:34816
	ds_read_b128 v[192:195], v204 offset:35840
	ds_read_b128 v[196:199], v204 offset:36864
	ds_read_b128 v[206:209], v204 offset:37888
	ds_read_b128 v[210:213], v204 offset:38912
	ds_read_b128 v[214:217], v204 offset:39936
	global_load_lds_dwordx4 v[228:229], off
	v_lshl_add_u64 v[228:229], s[36:37], 0, v[172:173]
	s_mov_b32 m0, s46
	s_nop 0
	global_load_lds_dwordx4 v[228:229], off
	s_waitcnt vmcnt(8)
	s_waitcnt lgkmcnt(0)
	s_barrier
	s_setprio 1
	s_waitcnt lgkmcnt(0)
	v_mfma_f32_16x16x32_bf16 v[158:161], v[66:69], v[162:165], v[158:161]
	v_mfma_f32_16x16x32_bf16 v[154:157], v[82:85], v[162:165], v[154:157]
	v_mfma_f32_16x16x32_bf16 v[142:145], v[66:69], v[188:191], v[142:145]
	v_mfma_f32_16x16x32_bf16 v[138:141], v[82:85], v[188:191], v[138:141]
	v_mfma_f32_16x16x32_bf16 v[114:117], v[66:69], v[196:199], v[114:117]
	v_mfma_f32_16x16x32_bf16 v[110:113], v[82:85], v[196:199], v[110:113]
	v_mfma_f32_16x16x32_bf16 v[90:93], v[66:69], v[210:213], v[90:93]
	v_mfma_f32_16x16x32_bf16 v[86:89], v[82:85], v[210:213], v[86:89]
	v_mfma_f32_16x16x32_bf16 v[158:161], v[70:73], v[166:169], v[158:161]
	v_mfma_f32_16x16x32_bf16 v[154:157], v[94:97], v[166:169], v[154:157]
	v_mfma_f32_16x16x32_bf16 v[142:145], v[70:73], v[192:195], v[142:145]
	v_mfma_f32_16x16x32_bf16 v[138:141], v[94:97], v[192:195], v[138:141]
	v_mfma_f32_16x16x32_bf16 v[114:117], v[70:73], v[206:209], v[114:117]
	v_mfma_f32_16x16x32_bf16 v[110:113], v[94:97], v[206:209], v[110:113]
	v_mfma_f32_16x16x32_bf16 v[90:93], v[70:73], v[214:217], v[90:93]
	v_mfma_f32_16x16x32_bf16 v[86:89], v[94:97], v[214:217], v[86:89]
	v_mfma_f32_16x16x32_bf16 v[150:153], v[106:109], v[162:165], v[150:153]
	v_mfma_f32_16x16x32_bf16 v[146:149], v[130:133], v[162:165], v[146:149]
	v_mfma_f32_16x16x32_bf16 v[126:129], v[106:109], v[188:191], v[126:129]
	v_mfma_f32_16x16x32_bf16 v[122:125], v[130:133], v[188:191], v[122:125]
	v_mfma_f32_16x16x32_bf16 v[102:105], v[106:109], v[196:199], v[102:105]
	v_mfma_f32_16x16x32_bf16 v[98:101], v[130:133], v[196:199], v[98:101]
	v_mfma_f32_16x16x32_bf16 v[78:81], v[106:109], v[210:213], v[78:81]
	v_mfma_f32_16x16x32_bf16 v[74:77], v[130:133], v[210:213], v[74:77]
	v_mfma_f32_16x16x32_bf16 v[150:153], v[118:121], v[166:169], v[150:153]
	v_mfma_f32_16x16x32_bf16 v[146:149], v[134:137], v[166:169], v[146:149]
	v_mfma_f32_16x16x32_bf16 v[126:129], v[118:121], v[192:195], v[126:129]
	v_mfma_f32_16x16x32_bf16 v[122:125], v[134:137], v[192:195], v[122:125]
	v_mfma_f32_16x16x32_bf16 v[102:105], v[118:121], v[206:209], v[102:105]
	v_mfma_f32_16x16x32_bf16 v[98:101], v[134:137], v[206:209], v[98:101]
	v_mfma_f32_16x16x32_bf16 v[78:81], v[118:121], v[214:217], v[78:81]
	v_mfma_f32_16x16x32_bf16 v[74:77], v[134:137], v[214:217], v[74:77]
	s_setprio 0
	s_barrier
; #define PG8_STAGE(bufoff, gbase, voff) do { _Pragma("unroll") for (int _i = 0; _i < 2; ++_i) \
;         __builtin_amdgcn_global_load_lds((const unsigned*)((const char*)(gbase) + (voff)[_i]), (PG8_LAS unsigned*)(lds + (bufoff) + ldsw + _i * 8192), 16, 0, 0); } while (0)
; #define PG8_LDA(dst, b, h) do { _Pragma("unroll") for (int m = 0; m < 4; ++m) _Pragma("unroll") for (int k = 0; k < 2; ++k) dst[m][k] = *(const PG8_LAS bf16x8*)(lds + PG8_SA(b, h) + aoff + m * 2048 + k * 1024); } while (0)
; #define PG8_MMA(ai, bj, At, Bt) do { __builtin_amdgcn_s_setprio(1); _Pragma("unroll") for (int m = 0; m < 4; ++m) _Pragma("unroll") for (int n = 0; n < 2; ++n) _Pragma("unroll") for (int k = 0; k < 2; ++k) \
;         acc[ai][bj][m][n] = __builtin_amdgcn_mfma_f32_16x16x32_bf16(Bt[n][k], At[m][k], acc[ai][bj][m][n], 0, 0, 0); __builtin_amdgcn_s_setprio(0); } while (0)
; #define PG8_WAIT_V(n) asm volatile("s_waitcnt vmcnt(" #n ")" ::: "memory")
; #define PG8_WAIT_L(n) asm volatile("s_waitcnt lgkmcnt(" #n ")" ::: "memory")
; #define PG8_BAR __builtin_amdgcn_s_barrier()
; #define PG8_SCHED __builtin_amdgcn_sched_barrier(0)
; template <class Epi, class Sched, bool ALIGN_EPI = false, bool SP2 = false>
; __device__ __forceinline__ void gemm_phase(PG8_LAS unsigned char* lds, const Gemm g, const Sched& S, const Epi& E) {
;     ...
;         for (int t = 0; t < nt; t += 2) {
;             const bool last = (t == nt - 2);
;             const char* a1 = cA + (size_t)(t + 1) * kstep;
;             const char* a2 = last ? nA : cA + (size_t)(t + 2) * kstep; const char* b2 = last ? nB : cB + (size_t)(t + 2) * kstep;
;             const char* a3 = a2 + kstep; const char* b3 = b2 + kstep;
;     ...
;             PG8_LDA(At, 1, 1); PG8_STAGE(PG8_SB(1, 0), b3, voffB); PG8_STAGE(PG8_SB(1, 1), b3 + hstep, voffB); PG8_STAGE(PG8_SA(1, 0), a3, voffA);
;             PG8_WAIT_V(8); PG8_WAIT_L(0); PG8_BAR; PG8_MMA(1, 0, At, B0); PG8_MMA(1, 1, At, B1); PG8_BAR; PG8_SCHED;
	s_add_i32 s36, s56, s42
	v_lshl_add_u64 v[200:201], v[200:201], 0, s[96:97]
	s_mov_b32 m0, s36
	ds_read_b128 v[162:165], v204 offset:49152
	ds_read_b128 v[166:169], v204 offset:50176
	ds_read_b128 v[188:191], v204 offset:51200
	ds_read_b128 v[192:195], v204 offset:52224
	ds_read_b128 v[196:199], v204 offset:53248
	ds_read_b128 v[206:209], v204 offset:54272
	ds_read_b128 v[210:213], v204 offset:55296
	ds_read_b128 v[214:217], v204 offset:56320
	global_load_lds_dwordx4 v[200:201], off
	s_add_i32 m0, s36, 0x2000
	s_add_u32 s10, s10, 0x40080
	v_lshl_add_u64 v[200:201], v[218:219], 0, s[96:97]
	s_addc_u32 s11, s11, 0
	s_add_i32 s36, s57, s42
	global_load_lds_dwordx4 v[200:201], off
	v_lshl_add_u64 v[200:201], s[10:11], 0, v[180:181]
	s_mov_b32 m0, s36
	s_nop 0
	global_load_lds_dwordx4 v[200:201], off
	v_lshl_add_u64 v[200:201], s[10:11], 0, v[170:171]
	s_add_i32 m0, s36, 0x2000
	s_nop 0
	global_load_lds_dwordx4 v[200:201], off
	v_lshl_add_u64 v[200:201], v[220:221], 0, s[96:97]
	s_mov_b32 m0, s50
	s_nop 0
	global_load_lds_dwordx4 v[200:201], off
	v_lshl_add_u64 v[200:201], v[222:223], 0, s[96:97]
	s_mov_b32 m0, s51
	s_nop 0
	global_load_lds_dwordx4 v[200:201], off
	s_add_i32 s55, s55, 2
	s_add_u32 s8, s8, 0x100
	s_addc_u32 s9, s9, 0
	s_add_u32 s33, s33, 0x100
	s_addc_u32 s54, s54, 0
	s_add_u32 s10, s8, 0xfffc0080
	s_addc_u32 s11, s9, -1
	s_add_i32 s56, 0, 0x10000
	s_cmp_eq_u32 s55, 12
	s_cselect_b32 s37, s5, s11
	s_cselect_b32 s36, s25, s10
	s_cselect_b32 s11, s27, s54
	s_cselect_b32 s10, s29, s33
	s_add_i32 s58, 0, 0x14000
	s_waitcnt vmcnt(8)
	s_waitcnt lgkmcnt(0)
	s_barrier
	s_setprio 1
	s_waitcnt lgkmcnt(0)
	v_mfma_f32_16x16x32_bf16 v[62:65], v[66:69], v[162:165], v[62:65]
	v_mfma_f32_16x16x32_bf16 v[58:61], v[82:85], v[162:165], v[58:61]
	v_mfma_f32_16x16x32_bf16 v[46:49], v[66:69], v[188:191], v[46:49]
	v_mfma_f32_16x16x32_bf16 v[42:45], v[82:85], v[188:191], v[42:45]
	v_mfma_f32_16x16x32_bf16 v[30:33], v[66:69], v[196:199], v[30:33]
	v_mfma_f32_16x16x32_bf16 v[26:29], v[82:85], v[196:199], v[26:29]
	v_mfma_f32_16x16x32_bf16 v[14:17], v[66:69], v[210:213], v[14:17]
	v_mfma_f32_16x16x32_bf16 v[10:13], v[82:85], v[210:213], v[10:13]
	v_mfma_f32_16x16x32_bf16 v[62:65], v[70:73], v[166:169], v[62:65]
	v_mfma_f32_16x16x32_bf16 v[58:61], v[94:97], v[166:169], v[58:61]
	v_mfma_f32_16x16x32_bf16 v[46:49], v[70:73], v[192:195], v[46:49]
	v_mfma_f32_16x16x32_bf16 v[42:45], v[94:97], v[192:195], v[42:45]
	v_mfma_f32_16x16x32_bf16 v[30:33], v[70:73], v[206:209], v[30:33]
	v_mfma_f32_16x16x32_bf16 v[26:29], v[94:97], v[206:209], v[26:29]
	v_mfma_f32_16x16x32_bf16 v[14:17], v[70:73], v[214:217], v[14:17]
	v_mfma_f32_16x16x32_bf16 v[10:13], v[94:97], v[214:217], v[10:13]
	v_mfma_f32_16x16x32_bf16 v[54:57], v[106:109], v[162:165], v[54:57]
	v_mfma_f32_16x16x32_bf16 v[50:53], v[130:133], v[162:165], v[50:53]
	v_mfma_f32_16x16x32_bf16 v[38:41], v[106:109], v[188:191], v[38:41]
	v_mfma_f32_16x16x32_bf16 v[34:37], v[130:133], v[188:191], v[34:37]
	v_mfma_f32_16x16x32_bf16 v[22:25], v[106:109], v[196:199], v[22:25]
	v_mfma_f32_16x16x32_bf16 v[18:21], v[130:133], v[196:199], v[18:21]
	v_mfma_f32_16x16x32_bf16 v[6:9], v[106:109], v[210:213], v[6:9]
	v_mfma_f32_16x16x32_bf16 v[2:5], v[130:133], v[210:213], v[2:5]
	v_mfma_f32_16x16x32_bf16 v[54:57], v[118:121], v[166:169], v[54:57]
	v_mfma_f32_16x16x32_bf16 v[50:53], v[134:137], v[166:169], v[50:53]
	v_mfma_f32_16x16x32_bf16 v[38:41], v[118:121], v[192:195], v[38:41]
	v_mfma_f32_16x16x32_bf16 v[34:37], v[134:137], v[192:195], v[34:37]
	v_mfma_f32_16x16x32_bf16 v[22:25], v[118:121], v[206:209], v[22:25]
	v_mfma_f32_16x16x32_bf16 v[18:21], v[134:137], v[206:209], v[18:21]
	v_mfma_f32_16x16x32_bf16 v[6:9], v[118:121], v[214:217], v[6:9]
	v_mfma_f32_16x16x32_bf16 v[2:5], v[134:137], v[214:217], v[2:5]
	s_setprio 0
	s_barrier
	s_cmp_gt_u32 s55, 13
	s_cbranch_scc0 .Lrot_evout
	s_and_b64 vcc, exec, s[20:21]
	s_cbranch_vccz .LBB0_1078
	s_barrier

; #define PG8_STAGE(bufoff, gbase, voff) do { _Pragma("unroll") for (int _i = 0; _i < 2; ++_i) \
;         __builtin_amdgcn_global_load_lds((const unsigned*)((const char*)(gbase) + (voff)[_i]), (PG8_LAS unsigned*)(lds + (bufoff) + ldsw + _i * 8192), 16, 0, 0); } while (0)
; #define PG8_LDA(dst, b, h) do { _Pragma("unroll") for (int m = 0; m < 4; ++m) _Pragma("unroll") for (int k = 0; k < 2; ++k) dst[m][k] = *(const PG8_LAS bf16x8*)(lds + PG8_SA(b, h) + aoff + m * 2048 + k * 1024); } while (0)
; #define PG8_LDB(dst, b, h) do { _Pragma("unroll") for (int n = 0; n < 2; ++n) _Pragma("unroll") for (int k = 0; k < 2; ++k) dst[n][k] = *(const PG8_LAS bf16x8*)(lds + PG8_SB(b, h) + boff + n * 2048 + k * 1024); } while (0)
; #define PG8_MMA(ai, bj, At, Bt) do { __builtin_amdgcn_s_setprio(1); _Pragma("unroll") for (int m = 0; m < 4; ++m) _Pragma("unroll") for (int n = 0; n < 2; ++n) _Pragma("unroll") for (int k = 0; k < 2; ++k) \
;         acc[ai][bj][m][n] = __builtin_amdgcn_mfma_f32_16x16x32_bf16(Bt[n][k], At[m][k], acc[ai][bj][m][n], 0, 0, 0); __builtin_amdgcn_s_setprio(0); } while (0)
; #define PG8_WAIT_V(n) asm volatile("s_waitcnt vmcnt(" #n ")" ::: "memory")
; #define PG8_WAIT_L(n) asm volatile("s_waitcnt lgkmcnt(" #n ")" ::: "memory")
; #define PG8_BAR __builtin_amdgcn_s_barrier()
; #define PG8_SCHED __builtin_amdgcn_sched_barrier(0)
; template <class Epi, class Sched, bool ALIGN_EPI = false, bool SP2 = false>
; __device__ __forceinline__ void gemm_phase(PG8_LAS unsigned char* lds, const Gemm g, const Sched& S, const Epi& E) {
;     ...
;             PG8_WAIT_V(8); PG8_WAIT_L(0); PG8_BAR; PG8_MMA(1, 0, At, B0); PG8_MMA(1, 1, At, B1); PG8_BAR; PG8_SCHED;
;             PG8_LDB(B0, 1, 0); PG8_LDB(B1, 1, 1); PG8_SCHED; PG8_LDA(At, 1, 0); PG8_STAGE(PG8_SA(0, 1), a2 + hstep, voffA);
;             PG8_WAIT_V(8); PG8_WAIT_L(0); PG8_BAR; PG8_MMA(0, 0, At, B0); PG8_MMA(0, 1, At, B1); PG8_BAR; PG8_SCHED;
.Lffin_wd:
	s_waitcnt lgkmcnt(0)
	s_barrier
	s_setprio 1
	s_waitcnt lgkmcnt(0)
	v_mfma_f32_16x16x32_bf16 v[62:65], v[106:109], v[162:165], v[62:65]
	v_mfma_f32_16x16x32_bf16 v[58:61], v[114:117], v[162:165], v[58:61]
	v_mfma_f32_16x16x32_bf16 v[46:49], v[106:109], v[170:173], v[46:49]
	v_mfma_f32_16x16x32_bf16 v[42:45], v[114:117], v[170:173], v[42:45]
	v_mfma_f32_16x16x32_bf16 v[30:33], v[106:109], v[196:199], v[30:33]
	v_mfma_f32_16x16x32_bf16 v[26:29], v[114:117], v[196:199], v[26:29]
	v_mfma_f32_16x16x32_bf16 v[14:17], v[106:109], v[204:207], v[14:17]
	v_mfma_f32_16x16x32_bf16 v[10:13], v[114:117], v[204:207], v[10:13]
	v_mfma_f32_16x16x32_bf16 v[62:65], v[110:113], v[166:169], v[62:65]
	v_mfma_f32_16x16x32_bf16 v[58:61], v[118:121], v[166:169], v[58:61]
	v_mfma_f32_16x16x32_bf16 v[46:49], v[110:113], v[192:195], v[46:49]
	v_mfma_f32_16x16x32_bf16 v[42:45], v[118:121], v[192:195], v[42:45]
	v_mfma_f32_16x16x32_bf16 v[30:33], v[110:113], v[200:203], v[30:33]
	v_mfma_f32_16x16x32_bf16 v[26:29], v[118:121], v[200:203], v[26:29]
	v_mfma_f32_16x16x32_bf16 v[14:17], v[110:113], v[208:211], v[14:17]
	v_mfma_f32_16x16x32_bf16 v[10:13], v[118:121], v[208:211], v[10:13]
	v_mfma_f32_16x16x32_bf16 v[54:57], v[122:125], v[162:165], v[54:57]
	v_mfma_f32_16x16x32_bf16 v[50:53], v[130:133], v[162:165], v[50:53]
	v_mfma_f32_16x16x32_bf16 v[38:41], v[122:125], v[170:173], v[38:41]
	v_mfma_f32_16x16x32_bf16 v[34:37], v[130:133], v[170:173], v[34:37]
	v_mfma_f32_16x16x32_bf16 v[22:25], v[122:125], v[196:199], v[22:25]
	v_mfma_f32_16x16x32_bf16 v[18:21], v[130:133], v[196:199], v[18:21]
	v_mfma_f32_16x16x32_bf16 v[6:9], v[122:125], v[204:207], v[6:9]
	v_mfma_f32_16x16x32_bf16 v[2:5], v[130:133], v[204:207], v[2:5]
	v_mfma_f32_16x16x32_bf16 v[54:57], v[126:129], v[166:169], v[54:57]
	v_mfma_f32_16x16x32_bf16 v[50:53], v[134:137], v[166:169], v[50:53]
	v_mfma_f32_16x16x32_bf16 v[38:41], v[126:129], v[192:195], v[38:41]
	v_mfma_f32_16x16x32_bf16 v[34:37], v[134:137], v[192:195], v[34:37]
	v_mfma_f32_16x16x32_bf16 v[22:25], v[126:129], v[200:203], v[22:25]
	v_mfma_f32_16x16x32_bf16 v[18:21], v[134:137], v[200:203], v[18:21]
	v_mfma_f32_16x16x32_bf16 v[6:9], v[126:129], v[208:211], v[6:9]
	v_mfma_f32_16x16x32_bf16 v[2:5], v[134:137], v[208:211], v[2:5]
	s_setprio 0
	s_barrier
	s_add_i32 s69, 0, 0x18000
	s_add_i32 s70, 0, 0x1c000
	v_add_u32_e32 v118, s69, v229
	v_add_u32_e32 v134, s70, v229
	ds_read_b128 v[106:109], v118
	ds_read_b128 v[110:113], v118 offset:1024
	ds_read_b128 v[114:117], v118 offset:2048
	ds_read_b128 v[118:121], v118 offset:3072
	ds_read_b128 v[122:125], v134
	ds_read_b128 v[126:129], v134 offset:1024
	ds_read_b128 v[130:133], v134 offset:2048
	ds_read_b128 v[134:137], v134 offset:3072
	s_add_u32 s46, s46, 0x40000
	s_addc_u32 s47, s47, 0
	s_mov_b32 m0, s55
	v_lshl_add_u64 v[220:221], s[46:47], 0, v[186:187]
	ds_read_b128 v[162:165], v230 offset:32768
	ds_read_b128 v[166:169], v230 offset:33792
	ds_read_b128 v[170:173], v230 offset:34816
	ds_read_b128 v[192:195], v230 offset:35840
	ds_read_b128 v[196:199], v230 offset:36864
	ds_read_b128 v[200:203], v230 offset:37888
	ds_read_b128 v[204:207], v230 offset:38912
	ds_read_b128 v[208:211], v230 offset:39936
	global_load_lds_dwordx4 v[220:221], off
	v_lshl_add_u64 v[220:221], s[46:47], 0, v[182:183]
	s_mov_b32 m0, s56
	s_nop 0
	global_load_lds_dwordx4 v[220:221], off
	s_waitcnt vmcnt(8)
	s_waitcnt lgkmcnt(0)
	s_barrier
	s_setprio 1
	s_waitcnt lgkmcnt(0)
	v_mfma_f32_16x16x32_bf16 v[158:161], v[106:109], v[162:165], v[158:161]
	v_mfma_f32_16x16x32_bf16 v[154:157], v[114:117], v[162:165], v[154:157]
	v_mfma_f32_16x16x32_bf16 v[142:145], v[106:109], v[170:173], v[142:145]
	v_mfma_f32_16x16x32_bf16 v[138:141], v[114:117], v[170:173], v[138:141]
	v_mfma_f32_16x16x32_bf16 v[94:97], v[106:109], v[196:199], v[94:97]
	v_mfma_f32_16x16x32_bf16 v[90:93], v[114:117], v[196:199], v[90:93]
	v_mfma_f32_16x16x32_bf16 v[78:81], v[106:109], v[204:207], v[78:81]
	v_mfma_f32_16x16x32_bf16 v[74:77], v[114:117], v[204:207], v[74:77]
	v_mfma_f32_16x16x32_bf16 v[158:161], v[110:113], v[166:169], v[158:161]
	v_mfma_f32_16x16x32_bf16 v[154:157], v[118:121], v[166:169], v[154:157]
	v_mfma_f32_16x16x32_bf16 v[142:145], v[110:113], v[192:195], v[142:145]
	v_mfma_f32_16x16x32_bf16 v[138:141], v[118:121], v[192:195], v[138:141]
	v_mfma_f32_16x16x32_bf16 v[94:97], v[110:113], v[200:203], v[94:97]
	v_mfma_f32_16x16x32_bf16 v[90:93], v[118:121], v[200:203], v[90:93]
	v_mfma_f32_16x16x32_bf16 v[78:81], v[110:113], v[208:211], v[78:81]
	v_mfma_f32_16x16x32_bf16 v[74:77], v[118:121], v[208:211], v[74:77]
	v_mfma_f32_16x16x32_bf16 v[150:153], v[122:125], v[162:165], v[150:153]
	v_mfma_f32_16x16x32_bf16 v[146:149], v[130:133], v[162:165], v[146:149]
	v_mfma_f32_16x16x32_bf16 v[102:105], v[122:125], v[170:173], v[102:105]
	v_mfma_f32_16x16x32_bf16 v[98:101], v[130:133], v[170:173], v[98:101]
	v_mfma_f32_16x16x32_bf16 v[86:89], v[122:125], v[196:199], v[86:89]
	v_mfma_f32_16x16x32_bf16 v[82:85], v[130:133], v[196:199], v[82:85]
	v_mfma_f32_16x16x32_bf16 v[70:73], v[122:125], v[204:207], v[70:73]
	v_mfma_f32_16x16x32_bf16 v[66:69], v[130:133], v[204:207], v[66:69]
	v_mfma_f32_16x16x32_bf16 v[150:153], v[126:129], v[166:169], v[150:153]
	v_mfma_f32_16x16x32_bf16 v[146:149], v[134:137], v[166:169], v[146:149]
	v_mfma_f32_16x16x32_bf16 v[102:105], v[126:129], v[192:195], v[102:105]
	v_mfma_f32_16x16x32_bf16 v[98:101], v[134:137], v[192:195], v[98:101]
	v_mfma_f32_16x16x32_bf16 v[86:89], v[126:129], v[200:203], v[86:89]
	v_mfma_f32_16x16x32_bf16 v[82:85], v[134:137], v[200:203], v[82:85]
	v_mfma_f32_16x16x32_bf16 v[70:73], v[126:129], v[208:211], v[70:73]
	v_mfma_f32_16x16x32_bf16 v[66:69], v[134:137], v[208:211], v[66:69]
	s_setprio 0
	s_barrier
; #define PG8_STAGE(bufoff, gbase, voff) do { _Pragma("unroll") for (int _i = 0; _i < 2; ++_i) \
;         __builtin_amdgcn_global_load_lds((const unsigned*)((const char*)(gbase) + (voff)[_i]), (PG8_LAS unsigned*)(lds + (bufoff) + ldsw + _i * 8192), 16, 0, 0); } while (0)
; #define PG8_LDA(dst, b, h) do { _Pragma("unroll") for (int m = 0; m < 4; ++m) _Pragma("unroll") for (int k = 0; k < 2; ++k) dst[m][k] = *(const PG8_LAS bf16x8*)(lds + PG8_SA(b, h) + aoff + m * 2048 + k * 1024); } while (0)
; #define PG8_MMA(ai, bj, At, Bt) do { __builtin_amdgcn_s_setprio(1); _Pragma("unroll") for (int m = 0; m < 4; ++m) _Pragma("unroll") for (int n = 0; n < 2; ++n) _Pragma("unroll") for (int k = 0; k < 2; ++k) \
;         acc[ai][bj][m][n] = __builtin_amdgcn_mfma_f32_16x16x32_bf16(Bt[n][k], At[m][k], acc[ai][bj][m][n], 0, 0, 0); __builtin_amdgcn_s_setprio(0); } while (0)
; #define PG8_WAIT_V(n) asm volatile("s_waitcnt vmcnt(" #n ")" ::: "memory")
; #define PG8_WAIT_L(n) asm volatile("s_waitcnt lgkmcnt(" #n ")" ::: "memory")
; #define PG8_BAR __builtin_amdgcn_s_barrier()
; #define PG8_SCHED __builtin_amdgcn_sched_barrier(0)
; template <class Epi, class Sched, bool ALIGN_EPI = false, bool SP2 = false>
; __device__ __forceinline__ void gemm_phase(PG8_LAS unsigned char* lds, const Gemm g, const Sched& S, const Epi& E) {
;     ...
;         for (int t = 0; t < nt; t += 2) {
;             const bool last = (t == nt - 2);
;             const char* a1 = cA + (size_t)(t + 1) * kstep;
;             const char* a2 = last ? nA : cA + (size_t)(t + 2) * kstep; const char* b2 = last ? nB : cB + (size_t)(t + 2) * kstep;
;             const char* a3 = a2 + kstep; const char* b3 = b2 + kstep;
;     ...
;             PG8_LDA(At, 1, 1); PG8_STAGE(PG8_SB(1, 0), b3, voffB); PG8_STAGE(PG8_SB(1, 1), b3 + hstep, voffB); PG8_STAGE(PG8_SA(1, 0), a3, voffA);
;             PG8_WAIT_V(8); PG8_WAIT_L(0); PG8_BAR; PG8_MMA(1, 0, At, B0); PG8_MMA(1, 1, At, B1); PG8_BAR; PG8_SCHED;
	s_add_i32 s46, s69, s52
	v_lshl_add_u64 v[212:213], v[212:213], 0, s[96:97]
	s_mov_b32 m0, s46
	ds_read_b128 v[162:165], v230 offset:49152
	ds_read_b128 v[166:169], v230 offset:50176
	ds_read_b128 v[170:173], v230 offset:51200
	ds_read_b128 v[192:195], v230 offset:52224
	ds_read_b128 v[196:199], v230 offset:53248
	ds_read_b128 v[200:203], v230 offset:54272
	ds_read_b128 v[204:207], v230 offset:55296
	ds_read_b128 v[208:211], v230 offset:56320
	global_load_lds_dwordx4 v[212:213], off
	s_add_i32 m0, s46, 0x2000
	s_add_u32 s44, s44, 0x40080
	v_lshl_add_u64 v[212:213], v[214:215], 0, s[96:97]
	s_addc_u32 s45, s45, 0
	s_add_i32 s46, s70, s52
	global_load_lds_dwordx4 v[212:213], off
	v_lshl_add_u64 v[212:213], s[44:45], 0, v[184:185]
	s_mov_b32 m0, s46
	s_nop 0
	global_load_lds_dwordx4 v[212:213], off
	v_lshl_add_u64 v[212:213], s[44:45], 0, v[180:181]
	s_add_i32 m0, s46, 0x2000
	s_nop 0
	global_load_lds_dwordx4 v[212:213], off
	v_lshl_add_u64 v[212:213], v[216:217], 0, s[96:97]
	s_mov_b32 m0, s60
	s_nop 0
	global_load_lds_dwordx4 v[212:213], off
	v_lshl_add_u64 v[212:213], v[218:219], 0, s[96:97]
	s_mov_b32 m0, s61
	s_nop 0
	global_load_lds_dwordx4 v[212:213], off
	s_add_i32 s68, s68, 2
	s_add_u32 s8, s8, 0x100
	s_addc_u32 s9, s9, 0
	s_add_u32 s66, s66, 0x100
	s_addc_u32 s67, s67, 0
	s_add_u32 s44, s8, 0xfffc0080
	s_addc_u32 s45, s9, -1
	s_add_i32 s69, 0, 0x10000
	s_cmp_eq_u32 s68, 12
	s_cselect_b32 s47, s37, s45
	s_cselect_b32 s46, s43, s44
	s_cselect_b32 s45, s35, s67
	s_cselect_b32 s44, s65, s66
	s_add_i32 s72, 0, 0x14000
	s_waitcnt vmcnt(8)
	s_waitcnt lgkmcnt(0)
	s_barrier
	s_setprio 1
	s_waitcnt lgkmcnt(0)
	v_mfma_f32_16x16x32_bf16 v[62:65], v[106:109], v[162:165], v[62:65]
	v_mfma_f32_16x16x32_bf16 v[58:61], v[114:117], v[162:165], v[58:61]
	v_mfma_f32_16x16x32_bf16 v[46:49], v[106:109], v[170:173], v[46:49]
	v_mfma_f32_16x16x32_bf16 v[42:45], v[114:117], v[170:173], v[42:45]
	v_mfma_f32_16x16x32_bf16 v[30:33], v[106:109], v[196:199], v[30:33]
	v_mfma_f32_16x16x32_bf16 v[26:29], v[114:117], v[196:199], v[26:29]
	v_mfma_f32_16x16x32_bf16 v[14:17], v[106:109], v[204:207], v[14:17]
	v_mfma_f32_16x16x32_bf16 v[10:13], v[114:117], v[204:207], v[10:13]
	v_mfma_f32_16x16x32_bf16 v[62:65], v[110:113], v[166:169], v[62:65]
	v_mfma_f32_16x16x32_bf16 v[58:61], v[118:121], v[166:169], v[58:61]
	v_mfma_f32_16x16x32_bf16 v[46:49], v[110:113], v[192:195], v[46:49]
	v_mfma_f32_16x16x32_bf16 v[42:45], v[118:121], v[192:195], v[42:45]
	v_mfma_f32_16x16x32_bf16 v[30:33], v[110:113], v[200:203], v[30:33]
	v_mfma_f32_16x16x32_bf16 v[26:29], v[118:121], v[200:203], v[26:29]
	v_mfma_f32_16x16x32_bf16 v[14:17], v[110:113], v[208:211], v[14:17]
	v_mfma_f32_16x16x32_bf16 v[10:13], v[118:121], v[208:211], v[10:13]
	v_mfma_f32_16x16x32_bf16 v[54:57], v[122:125], v[162:165], v[54:57]
	v_mfma_f32_16x16x32_bf16 v[50:53], v[130:133], v[162:165], v[50:53]
	v_mfma_f32_16x16x32_bf16 v[38:41], v[122:125], v[170:173], v[38:41]
	v_mfma_f32_16x16x32_bf16 v[34:37], v[130:133], v[170:173], v[34:37]
	v_mfma_f32_16x16x32_bf16 v[22:25], v[122:125], v[196:199], v[22:25]
	v_mfma_f32_16x16x32_bf16 v[18:21], v[130:133], v[196:199], v[18:21]
	v_mfma_f32_16x16x32_bf16 v[6:9], v[122:125], v[204:207], v[6:9]
	v_mfma_f32_16x16x32_bf16 v[2:5], v[130:133], v[204:207], v[2:5]
	v_mfma_f32_16x16x32_bf16 v[54:57], v[126:129], v[166:169], v[54:57]
	v_mfma_f32_16x16x32_bf16 v[50:53], v[134:137], v[166:169], v[50:53]
	v_mfma_f32_16x16x32_bf16 v[38:41], v[126:129], v[192:195], v[38:41]
	v_mfma_f32_16x16x32_bf16 v[34:37], v[134:137], v[192:195], v[34:37]
	v_mfma_f32_16x16x32_bf16 v[22:25], v[126:129], v[200:203], v[22:25]
	v_mfma_f32_16x16x32_bf16 v[18:21], v[134:137], v[200:203], v[18:21]
	v_mfma_f32_16x16x32_bf16 v[6:9], v[126:129], v[208:211], v[6:9]
	v_mfma_f32_16x16x32_bf16 v[2:5], v[134:137], v[208:211], v[2:5]
	s_setprio 0
	s_barrier
	s_cmp_gt_u32 s68, 13
	s_cbranch_scc0 .Lrot_ffin
	s_and_b64 vcc, exec, s[24:25]
	s_cbranch_vccz .LBB0_1250
	s_barrier

; #define PG8_STAGE(bufoff, gbase, voff) do { _Pragma("unroll") for (int _i = 0; _i < 2; ++_i) \
;         __builtin_amdgcn_global_load_lds((const unsigned*)((const char*)(gbase) + (voff)[_i]), (PG8_LAS unsigned*)(lds + (bufoff) + ldsw + _i * 8192), 16, 0, 0); } while (0)
; #define PG8_LDA(dst, b, h) do { _Pragma("unroll") for (int m = 0; m < 4; ++m) _Pragma("unroll") for (int k = 0; k < 2; ++k) dst[m][k] = *(const PG8_LAS bf16x8*)(lds + PG8_SA(b, h) + aoff + m * 2048 + k * 1024); } while (0)
; #define PG8_MMA(ai, bj, At, Bt) do { __builtin_amdgcn_s_setprio(1); _Pragma("unroll") for (int m = 0; m < 4; ++m) _Pragma("unroll") for (int n = 0; n < 2; ++n) _Pragma("unroll") for (int k = 0; k < 2; ++k) \
;         acc[ai][bj][m][n] = __builtin_amdgcn_mfma_f32_16x16x32_bf16(Bt[n][k], At[m][k], acc[ai][bj][m][n], 0, 0, 0); __builtin_amdgcn_s_setprio(0); } while (0)
; #define PG8_WAIT_V(n) asm volatile("s_waitcnt vmcnt(" #n ")" ::: "memory")
; #define PG8_WAIT_L(n) asm volatile("s_waitcnt lgkmcnt(" #n ")" ::: "memory")
; #define PG8_BAR __builtin_amdgcn_s_barrier()
; #define PG8_SCHED __builtin_amdgcn_sched_barrier(0)
; template <class Epi, class Sched, bool ALIGN_EPI = false, bool SP2 = false>
; __device__ __forceinline__ void gemm_phase(PG8_LAS unsigned char* lds, const Gemm g, const Sched& S, const Epi& E) {
;     ...
;             PG8_WAIT_V(8); PG8_WAIT_L(0); PG8_BAR; PG8_MMA(0, 0, At, B0); PG8_MMA(0, 1, At, B1); PG8_BAR; PG8_SCHED;
;             PG8_LDA(At, 0, 1); PG8_STAGE(PG8_SB(0, 0), b2, voffB); PG8_STAGE(PG8_SB(0, 1), b2 + hstep, voffB); PG8_STAGE(PG8_SA(0, 0), a2, voffA);
;             PG8_WAIT_V(8); PG8_WAIT_L(0); PG8_BAR; PG8_MMA(1, 0, At, B0); PG8_MMA(1, 1, At, B1); PG8_BAR; PG8_SCHED;
.Lffout_noz:
	s_waitcnt vmcnt(8)
	s_waitcnt lgkmcnt(0)
	s_barrier
	s_setprio 1
	s_waitcnt lgkmcnt(0)
	v_mfma_f32_16x16x32_bf16 v[142:145], v[114:117], v[180:183], v[142:145]
	v_mfma_f32_16x16x32_bf16 v[138:141], v[122:125], v[180:183], v[138:141]
	v_mfma_f32_16x16x32_bf16 v[110:113], v[114:117], v[192:195], v[110:113]
	v_mfma_f32_16x16x32_bf16 v[106:109], v[122:125], v[192:195], v[106:109]
	v_mfma_f32_16x16x32_bf16 v[94:97], v[114:117], v[200:203], v[94:97]
	v_mfma_f32_16x16x32_bf16 v[90:93], v[122:125], v[200:203], v[90:93]
	v_mfma_f32_16x16x32_bf16 v[78:81], v[114:117], v[208:211], v[78:81]
	v_mfma_f32_16x16x32_bf16 v[74:77], v[122:125], v[208:211], v[74:77]
	v_mfma_f32_16x16x32_bf16 v[142:145], v[118:121], v[188:191], v[142:145]
	v_mfma_f32_16x16x32_bf16 v[138:141], v[134:137], v[188:191], v[138:141]
	v_mfma_f32_16x16x32_bf16 v[110:113], v[118:121], v[196:199], v[110:113]
	v_mfma_f32_16x16x32_bf16 v[106:109], v[134:137], v[196:199], v[106:109]
	v_mfma_f32_16x16x32_bf16 v[94:97], v[118:121], v[204:207], v[94:97]
	v_mfma_f32_16x16x32_bf16 v[90:93], v[134:137], v[204:207], v[90:93]
	v_mfma_f32_16x16x32_bf16 v[78:81], v[118:121], v[212:215], v[78:81]
	v_mfma_f32_16x16x32_bf16 v[74:77], v[134:137], v[212:215], v[74:77]
	v_mfma_f32_16x16x32_bf16 v[130:133], v[146:149], v[180:183], v[130:133]
	v_mfma_f32_16x16x32_bf16 v[126:129], v[166:169], v[180:183], v[126:129]
	v_mfma_f32_16x16x32_bf16 v[102:105], v[146:149], v[192:195], v[102:105]
	v_mfma_f32_16x16x32_bf16 v[98:101], v[166:169], v[192:195], v[98:101]
	v_mfma_f32_16x16x32_bf16 v[86:89], v[146:149], v[200:203], v[86:89]
	v_mfma_f32_16x16x32_bf16 v[82:85], v[166:169], v[200:203], v[82:85]
	v_mfma_f32_16x16x32_bf16 v[70:73], v[146:149], v[208:211], v[70:73]
	v_mfma_f32_16x16x32_bf16 v[66:69], v[166:169], v[208:211], v[66:69]
	v_mfma_f32_16x16x32_bf16 v[130:133], v[150:153], v[188:191], v[130:133]
	v_mfma_f32_16x16x32_bf16 v[126:129], v[170:173], v[188:191], v[126:129]
	v_mfma_f32_16x16x32_bf16 v[102:105], v[150:153], v[196:199], v[102:105]
	v_mfma_f32_16x16x32_bf16 v[98:101], v[170:173], v[196:199], v[98:101]
	v_mfma_f32_16x16x32_bf16 v[86:89], v[150:153], v[204:207], v[86:89]
	v_mfma_f32_16x16x32_bf16 v[82:85], v[170:173], v[204:207], v[82:85]
	v_mfma_f32_16x16x32_bf16 v[70:73], v[150:153], v[212:215], v[70:73]
	v_mfma_f32_16x16x32_bf16 v[66:69], v[170:173], v[212:215], v[66:69]
	s_setprio 0
	s_barrier
	s_add_i32 s22, s51, s34
	v_lshl_add_u64 v[216:217], s[24:25], 0, v[158:159]
	s_mov_b32 m0, s22
	ds_read_b128 v[180:183], v186 offset:16384
	ds_read_b128 v[188:191], v186 offset:17408
	ds_read_b128 v[192:195], v186 offset:18432
	ds_read_b128 v[196:199], v186 offset:19456
	ds_read_b128 v[200:203], v186 offset:20480
	ds_read_b128 v[204:207], v186 offset:21504
	ds_read_b128 v[208:211], v186 offset:22528
	ds_read_b128 v[212:215], v186 offset:23552
	global_load_lds_dwordx4 v[216:217], off
	s_add_i32 m0, s22, 0x2000
	s_add_u32 s22, s24, 0xb0000
	v_lshl_add_u64 v[218:219], s[24:25], 0, v[154:155]
	s_addc_u32 s23, s25, 0
	s_add_i32 s51, s52, s34
	global_load_lds_dwordx4 v[218:219], off
	v_lshl_add_u64 v[220:221], s[22:23], 0, v[158:159]
	s_mov_b32 m0, s51
	v_lshl_add_u64 v[222:223], s[26:27], 0, v[156:157]
	global_load_lds_dwordx4 v[220:221], off
	v_lshl_add_u64 v[220:221], s[22:23], 0, v[154:155]
	s_add_i32 m0, s51, 0x2000
	s_nop 0
	global_load_lds_dwordx4 v[220:221], off
	v_lshl_add_u64 v[220:221], s[26:27], 0, v[160:161]
	s_mov_b32 m0, s35
	s_nop 0
	global_load_lds_dwordx4 v[220:221], off
	s_mov_b32 m0, s36
	s_nop 0
	global_load_lds_dwordx4 v[222:223], off
	s_waitcnt vmcnt(8)
	s_waitcnt lgkmcnt(0)
	s_barrier
	s_setprio 1
	s_waitcnt lgkmcnt(0)
	v_mfma_f32_16x16x32_bf16 v[62:65], v[114:117], v[180:183], v[62:65]
	v_mfma_f32_16x16x32_bf16 v[58:61], v[122:125], v[180:183], v[58:61]
	v_mfma_f32_16x16x32_bf16 v[46:49], v[114:117], v[192:195], v[46:49]
	v_mfma_f32_16x16x32_bf16 v[42:45], v[122:125], v[192:195], v[42:45]
	v_mfma_f32_16x16x32_bf16 v[30:33], v[114:117], v[200:203], v[30:33]
	v_mfma_f32_16x16x32_bf16 v[26:29], v[122:125], v[200:203], v[26:29]
	v_mfma_f32_16x16x32_bf16 v[14:17], v[114:117], v[208:211], v[14:17]
	v_mfma_f32_16x16x32_bf16 v[10:13], v[122:125], v[208:211], v[10:13]
	v_mfma_f32_16x16x32_bf16 v[62:65], v[118:121], v[188:191], v[62:65]
	v_mfma_f32_16x16x32_bf16 v[58:61], v[134:137], v[188:191], v[58:61]
	v_mfma_f32_16x16x32_bf16 v[46:49], v[118:121], v[196:199], v[46:49]
	v_mfma_f32_16x16x32_bf16 v[42:45], v[134:137], v[196:199], v[42:45]
	v_mfma_f32_16x16x32_bf16 v[30:33], v[118:121], v[204:207], v[30:33]
	v_mfma_f32_16x16x32_bf16 v[26:29], v[134:137], v[204:207], v[26:29]
	v_mfma_f32_16x16x32_bf16 v[14:17], v[118:121], v[212:215], v[14:17]
	v_mfma_f32_16x16x32_bf16 v[10:13], v[134:137], v[212:215], v[10:13]
	v_mfma_f32_16x16x32_bf16 v[54:57], v[146:149], v[180:183], v[54:57]
	v_mfma_f32_16x16x32_bf16 v[50:53], v[166:169], v[180:183], v[50:53]
	v_mfma_f32_16x16x32_bf16 v[38:41], v[146:149], v[192:195], v[38:41]
	v_mfma_f32_16x16x32_bf16 v[34:37], v[166:169], v[192:195], v[34:37]
	v_mfma_f32_16x16x32_bf16 v[22:25], v[146:149], v[200:203], v[22:25]
	v_mfma_f32_16x16x32_bf16 v[18:21], v[166:169], v[200:203], v[18:21]
	v_mfma_f32_16x16x32_bf16 v[6:9], v[146:149], v[208:211], v[6:9]
	v_mfma_f32_16x16x32_bf16 v[2:5], v[166:169], v[208:211], v[2:5]
	v_mfma_f32_16x16x32_bf16 v[54:57], v[150:153], v[188:191], v[54:57]
	v_mfma_f32_16x16x32_bf16 v[50:53], v[170:173], v[188:191], v[50:53]
	v_mfma_f32_16x16x32_bf16 v[38:41], v[150:153], v[196:199], v[38:41]
	v_mfma_f32_16x16x32_bf16 v[34:37], v[170:173], v[196:199], v[34:37]
	v_mfma_f32_16x16x32_bf16 v[22:25], v[150:153], v[204:207], v[22:25]
	v_mfma_f32_16x16x32_bf16 v[18:21], v[170:173], v[204:207], v[18:21]
	v_mfma_f32_16x16x32_bf16 v[6:9], v[150:153], v[212:215], v[6:9]
	v_mfma_f32_16x16x32_bf16 v[2:5], v[170:173], v[212:215], v[2:5]
	s_setprio 0
	s_barrier
; #define PG8_STAGE(bufoff, gbase, voff) do { _Pragma("unroll") for (int _i = 0; _i < 2; ++_i) \
;         __builtin_amdgcn_global_load_lds((const unsigned*)((const char*)(gbase) + (voff)[_i]), (PG8_LAS unsigned*)(lds + (bufoff) + ldsw + _i * 8192), 16, 0, 0); } while (0)
; #define PG8_LDA(dst, b, h) do { _Pragma("unroll") for (int m = 0; m < 4; ++m) _Pragma("unroll") for (int k = 0; k < 2; ++k) dst[m][k] = *(const PG8_LAS bf16x8*)(lds + PG8_SA(b, h) + aoff + m * 2048 + k * 1024); } while (0)
; #define PG8_LDB(dst, b, h) do { _Pragma("unroll") for (int n = 0; n < 2; ++n) _Pragma("unroll") for (int k = 0; k < 2; ++k) dst[n][k] = *(const PG8_LAS bf16x8*)(lds + PG8_SB(b, h) + boff + n * 2048 + k * 1024); } while (0)
; #define PG8_MMA(ai, bj, At, Bt) do { __builtin_amdgcn_s_setprio(1); _Pragma("unroll") for (int m = 0; m < 4; ++m) _Pragma("unroll") for (int n = 0; n < 2; ++n) _Pragma("unroll") for (int k = 0; k < 2; ++k) \
;         acc[ai][bj][m][n] = __builtin_amdgcn_mfma_f32_16x16x32_bf16(Bt[n][k], At[m][k], acc[ai][bj][m][n], 0, 0, 0); __builtin_amdgcn_s_setprio(0); } while (0)
; #define PG8_WAIT_V(n) asm volatile("s_waitcnt vmcnt(" #n ")" ::: "memory")
; #define PG8_WAIT_L(n) asm volatile("s_waitcnt lgkmcnt(" #n ")" ::: "memory")
; #define PG8_BAR __builtin_amdgcn_s_barrier()
; #define PG8_SCHED __builtin_amdgcn_sched_barrier(0)
; template <class Epi, class Sched, bool ALIGN_EPI = false, bool SP2 = false>
; __device__ __forceinline__ void gemm_phase(PG8_LAS unsigned char* lds, const Gemm g, const Sched& S, const Epi& E) {
;     ...
;             PG8_LDB(B0, 1, 0); PG8_LDB(B1, 1, 1); PG8_SCHED; PG8_LDA(At, 1, 0); PG8_STAGE(PG8_SA(0, 1), a2 + hstep, voffA);
;             PG8_WAIT_V(8); PG8_WAIT_L(0); PG8_BAR; PG8_MMA(0, 0, At, B0); PG8_MMA(0, 1, At, B1); PG8_BAR; PG8_SCHED;
	s_add_i32 s51, 0, 0x18000
	s_add_i32 s52, 0, 0x1c000
	v_add_u32_e32 v134, s51, v185
	v_add_u32_e32 v170, s52, v185
	ds_read_b128 v[114:117], v134
	ds_read_b128 v[118:121], v134 offset:1024
	ds_read_b128 v[122:125], v134 offset:2048
	ds_read_b128 v[134:137], v134 offset:3072
	ds_read_b128 v[146:149], v170
	ds_read_b128 v[150:153], v170 offset:1024
	ds_read_b128 v[166:169], v170 offset:2048
	ds_read_b128 v[170:173], v170 offset:3072
	s_add_u32 s22, s26, 0xb0000
	s_addc_u32 s23, s27, 0
	s_mov_b32 m0, s37
	v_lshl_add_u64 v[228:229], s[22:23], 0, v[160:161]
	ds_read_b128 v[180:183], v186 offset:32768
	ds_read_b128 v[188:191], v186 offset:33792
	ds_read_b128 v[192:195], v186 offset:34816
	ds_read_b128 v[196:199], v186 offset:35840
	ds_read_b128 v[200:203], v186 offset:36864
	ds_read_b128 v[204:207], v186 offset:37888
	ds_read_b128 v[208:211], v186 offset:38912
	ds_read_b128 v[212:215], v186 offset:39936
	global_load_lds_dwordx4 v[228:229], off
	v_lshl_add_u64 v[228:229], s[22:23], 0, v[156:157]
	s_mov_b32 m0, s38
	s_nop 0
	global_load_lds_dwordx4 v[228:229], off
	s_waitcnt vmcnt(8)
	s_waitcnt lgkmcnt(0)
	s_barrier
	s_setprio 1
	s_waitcnt lgkmcnt(0)
	v_mfma_f32_16x16x32_bf16 v[142:145], v[114:117], v[180:183], v[142:145]
	v_mfma_f32_16x16x32_bf16 v[138:141], v[122:125], v[180:183], v[138:141]
	v_mfma_f32_16x16x32_bf16 v[110:113], v[114:117], v[192:195], v[110:113]
	v_mfma_f32_16x16x32_bf16 v[106:109], v[122:125], v[192:195], v[106:109]
	v_mfma_f32_16x16x32_bf16 v[94:97], v[114:117], v[200:203], v[94:97]
	v_mfma_f32_16x16x32_bf16 v[90:93], v[122:125], v[200:203], v[90:93]
	v_mfma_f32_16x16x32_bf16 v[78:81], v[114:117], v[208:211], v[78:81]
	v_mfma_f32_16x16x32_bf16 v[74:77], v[122:125], v[208:211], v[74:77]
	v_mfma_f32_16x16x32_bf16 v[142:145], v[118:121], v[188:191], v[142:145]
	v_mfma_f32_16x16x32_bf16 v[138:141], v[134:137], v[188:191], v[138:141]
	v_mfma_f32_16x16x32_bf16 v[110:113], v[118:121], v[196:199], v[110:113]
	v_mfma_f32_16x16x32_bf16 v[106:109], v[134:137], v[196:199], v[106:109]
	v_mfma_f32_16x16x32_bf16 v[94:97], v[118:121], v[204:207], v[94:97]
	v_mfma_f32_16x16x32_bf16 v[90:93], v[134:137], v[204:207], v[90:93]
	v_mfma_f32_16x16x32_bf16 v[78:81], v[118:121], v[212:215], v[78:81]
	v_mfma_f32_16x16x32_bf16 v[74:77], v[134:137], v[212:215], v[74:77]
	v_mfma_f32_16x16x32_bf16 v[130:133], v[146:149], v[180:183], v[130:133]
	v_mfma_f32_16x16x32_bf16 v[126:129], v[166:169], v[180:183], v[126:129]
	v_mfma_f32_16x16x32_bf16 v[102:105], v[146:149], v[192:195], v[102:105]
	v_mfma_f32_16x16x32_bf16 v[98:101], v[166:169], v[192:195], v[98:101]
	v_mfma_f32_16x16x32_bf16 v[86:89], v[146:149], v[200:203], v[86:89]
	v_mfma_f32_16x16x32_bf16 v[82:85], v[166:169], v[200:203], v[82:85]
	v_mfma_f32_16x16x32_bf16 v[70:73], v[146:149], v[208:211], v[70:73]
	v_mfma_f32_16x16x32_bf16 v[66:69], v[166:169], v[208:211], v[66:69]
	v_mfma_f32_16x16x32_bf16 v[130:133], v[150:153], v[188:191], v[130:133]
	v_mfma_f32_16x16x32_bf16 v[126:129], v[170:173], v[188:191], v[126:129]
	v_mfma_f32_16x16x32_bf16 v[102:105], v[150:153], v[196:199], v[102:105]
	v_mfma_f32_16x16x32_bf16 v[98:101], v[170:173], v[196:199], v[98:101]
	v_mfma_f32_16x16x32_bf16 v[86:89], v[150:153], v[204:207], v[86:89]
	v_mfma_f32_16x16x32_bf16 v[82:85], v[170:173], v[204:207], v[82:85]
	v_mfma_f32_16x16x32_bf16 v[70:73], v[150:153], v[212:215], v[70:73]
	v_mfma_f32_16x16x32_bf16 v[66:69], v[170:173], v[212:215], v[66:69]
	s_setprio 0
	s_barrier
; #define PG8_STAGE(bufoff, gbase, voff) do { _Pragma("unroll") for (int _i = 0; _i < 2; ++_i) \
;         __builtin_amdgcn_global_load_lds((const unsigned*)((const char*)(gbase) + (voff)[_i]), (PG8_LAS unsigned*)(lds + (bufoff) + ldsw + _i * 8192), 16, 0, 0); } while (0)
; #define PG8_LDA(dst, b, h) do { _Pragma("unroll") for (int m = 0; m < 4; ++m) _Pragma("unroll") for (int k = 0; k < 2; ++k) dst[m][k] = *(const PG8_LAS bf16x8*)(lds + PG8_SA(b, h) + aoff + m * 2048 + k * 1024); } while (0)
; #define PG8_MMA(ai, bj, At, Bt) do { __builtin_amdgcn_s_setprio(1); _Pragma("unroll") for (int m = 0; m < 4; ++m) _Pragma("unroll") for (int n = 0; n < 2; ++n) _Pragma("unroll") for (int k = 0; k < 2; ++k) \
;         acc[ai][bj][m][n] = __builtin_amdgcn_mfma_f32_16x16x32_bf16(Bt[n][k], At[m][k], acc[ai][bj][m][n], 0, 0, 0); __builtin_amdgcn_s_setprio(0); } while (0)
; #define PG8_WAIT_V(n) asm volatile("s_waitcnt vmcnt(" #n ")" ::: "memory")
; #define PG8_WAIT_L(n) asm volatile("s_waitcnt lgkmcnt(" #n ")" ::: "memory")
; #define PG8_BAR __builtin_amdgcn_s_barrier()
; #define PG8_SCHED __builtin_amdgcn_sched_barrier(0)
; template <class Epi, class Sched, bool ALIGN_EPI = false, bool SP2 = false>
; __device__ __forceinline__ void gemm_phase(PG8_LAS unsigned char* lds, const Gemm g, const Sched& S, const Epi& E) {
;     ...
;         for (int t = 0; t < nt; t += 2) {
;             const bool last = (t == nt - 2);
;             const char* a1 = cA + (size_t)(t + 1) * kstep;
;             const char* a2 = last ? nA : cA + (size_t)(t + 2) * kstep; const char* b2 = last ? nB : cB + (size_t)(t + 2) * kstep;
;             const char* a3 = a2 + kstep; const char* b3 = b2 + kstep;
;     ...
;             PG8_LDA(At, 1, 1); PG8_STAGE(PG8_SB(1, 0), b3, voffB); PG8_STAGE(PG8_SB(1, 1), b3 + hstep, voffB); PG8_STAGE(PG8_SA(1, 0), a3, voffA);
;             PG8_WAIT_V(8); PG8_WAIT_L(0); PG8_BAR; PG8_MMA(1, 0, At, B0); PG8_MMA(1, 1, At, B1); PG8_BAR; PG8_SCHED;
	s_add_i32 s22, s51, s34
	v_lshl_add_u64 v[216:217], v[216:217], 0, s[96:97]
	s_mov_b32 m0, s22
	ds_read_b128 v[180:183], v186 offset:49152
	ds_read_b128 v[188:191], v186 offset:50176
	ds_read_b128 v[192:195], v186 offset:51200
	ds_read_b128 v[196:199], v186 offset:52224
	ds_read_b128 v[200:203], v186 offset:53248
	ds_read_b128 v[204:207], v186 offset:54272
	ds_read_b128 v[208:211], v186 offset:55296
	ds_read_b128 v[212:215], v186 offset:56320
	global_load_lds_dwordx4 v[216:217], off
	s_add_i32 m0, s22, 0x2000
	s_add_u32 s22, s24, 0xb0080
	v_lshl_add_u64 v[216:217], v[218:219], 0, s[96:97]
	s_addc_u32 s23, s25, 0
	s_add_i32 s24, s52, s34
	global_load_lds_dwordx4 v[216:217], off
	v_lshl_add_u64 v[216:217], s[22:23], 0, v[158:159]
	s_mov_b32 m0, s24
	s_nop 0
	global_load_lds_dwordx4 v[216:217], off
	v_lshl_add_u64 v[216:217], s[22:23], 0, v[154:155]
	s_add_i32 m0, s24, 0x2000
	s_nop 0
	global_load_lds_dwordx4 v[216:217], off
	v_lshl_add_u64 v[216:217], v[220:221], 0, s[96:97]
	s_mov_b32 m0, s41
	s_nop 0
	global_load_lds_dwordx4 v[216:217], off
	v_lshl_add_u64 v[216:217], v[222:223], 0, s[96:97]
	s_mov_b32 m0, s42
	s_nop 0
	global_load_lds_dwordx4 v[216:217], off
	s_add_i32 s50, s50, 2
	s_add_u32 s33, s33, 0x100
	s_addc_u32 s49, s49, 0
	s_mov_b64 s[22:23], s[8:9]
	s_add_u32 s8, s22, 0x100
	s_addc_u32 s9, s23, 0
	s_add_i32 s51, 0, 0x10000
	s_cmp_eq_u32 s50, 40
	s_cselect_b32 s27, s19, s9
	s_cselect_b32 s26, s18, s8
	s_cselect_b32 s25, s21, s49
	s_cselect_b32 s24, s20, s33
	s_add_i32 s52, 0, 0x14000
	s_waitcnt vmcnt(8)
	s_waitcnt lgkmcnt(0)
	s_barrier
	s_setprio 1
	s_waitcnt lgkmcnt(0)
	v_mfma_f32_16x16x32_bf16 v[62:65], v[114:117], v[180:183], v[62:65]
	v_mfma_f32_16x16x32_bf16 v[58:61], v[122:125], v[180:183], v[58:61]
	v_mfma_f32_16x16x32_bf16 v[46:49], v[114:117], v[192:195], v[46:49]
	v_mfma_f32_16x16x32_bf16 v[42:45], v[122:125], v[192:195], v[42:45]
	v_mfma_f32_16x16x32_bf16 v[30:33], v[114:117], v[200:203], v[30:33]
	v_mfma_f32_16x16x32_bf16 v[26:29], v[122:125], v[200:203], v[26:29]
	v_mfma_f32_16x16x32_bf16 v[14:17], v[114:117], v[208:211], v[14:17]
	v_mfma_f32_16x16x32_bf16 v[10:13], v[122:125], v[208:211], v[10:13]
	v_mfma_f32_16x16x32_bf16 v[62:65], v[118:121], v[188:191], v[62:65]
	v_mfma_f32_16x16x32_bf16 v[58:61], v[134:137], v[188:191], v[58:61]
	v_mfma_f32_16x16x32_bf16 v[46:49], v[118:121], v[196:199], v[46:49]
	v_mfma_f32_16x16x32_bf16 v[42:45], v[134:137], v[196:199], v[42:45]
	v_mfma_f32_16x16x32_bf16 v[30:33], v[118:121], v[204:207], v[30:33]
	v_mfma_f32_16x16x32_bf16 v[26:29], v[134:137], v[204:207], v[26:29]
	v_mfma_f32_16x16x32_bf16 v[14:17], v[118:121], v[212:215], v[14:17]
	v_mfma_f32_16x16x32_bf16 v[10:13], v[134:137], v[212:215], v[10:13]
	v_mfma_f32_16x16x32_bf16 v[54:57], v[146:149], v[180:183], v[54:57]
	v_mfma_f32_16x16x32_bf16 v[50:53], v[166:169], v[180:183], v[50:53]
	v_mfma_f32_16x16x32_bf16 v[38:41], v[146:149], v[192:195], v[38:41]
	v_mfma_f32_16x16x32_bf16 v[34:37], v[166:169], v[192:195], v[34:37]
	v_mfma_f32_16x16x32_bf16 v[22:25], v[146:149], v[200:203], v[22:25]
	v_mfma_f32_16x16x32_bf16 v[18:21], v[166:169], v[200:203], v[18:21]
	v_mfma_f32_16x16x32_bf16 v[6:9], v[146:149], v[208:211], v[6:9]
	v_mfma_f32_16x16x32_bf16 v[2:5], v[166:169], v[208:211], v[2:5]
	v_mfma_f32_16x16x32_bf16 v[54:57], v[150:153], v[188:191], v[54:57]
	v_mfma_f32_16x16x32_bf16 v[50:53], v[170:173], v[188:191], v[50:53]
	v_mfma_f32_16x16x32_bf16 v[38:41], v[150:153], v[196:199], v[38:41]
	v_mfma_f32_16x16x32_bf16 v[34:37], v[170:173], v[196:199], v[34:37]
	v_mfma_f32_16x16x32_bf16 v[22:25], v[150:153], v[204:207], v[22:25]
	v_mfma_f32_16x16x32_bf16 v[18:21], v[170:173], v[204:207], v[18:21]
	v_mfma_f32_16x16x32_bf16 v[6:9], v[150:153], v[212:215], v[6:9]
	v_mfma_f32_16x16x32_bf16 v[2:5], v[170:173], v[212:215], v[2:5]
	s_setprio 0
	s_barrier
	s_cmp_gt_u32 s50, 41
	s_cbranch_scc0 .Lrot_ffout
	s_and_b64 vcc, exec, s[14:15]
	s_cbranch_vccz .LBB0_1363
	s_barrier
